# GEMM loops: LDS-DMA pieces use the saddr form (SGPR base + 32-bit lane offset); 40 per-piece v_lshl_add_u64 removed from the load segments
# speedup vs baseline: 1.0390x; 1.0057x over previous
; #define PG8_STAGE(bufoff, gbase, voff) do { _Pragma("unroll") for (int _i = 0; _i < 2; ++_i) \
;         __builtin_amdgcn_global_load_lds((const unsigned*)((const char*)(gbase) + (voff)[_i]), (LAS unsigned*)(lds + (bufoff) + ldsw + _i * 8192), 16, 0, 0); } while (0)
; #define PG8_LDA(dst, b, h) do { _Pragma("unroll") for (int m = 0; m < 4; ++m) _Pragma("unroll") for (int k = 0; k < 2; ++k) dst[m][k] = *(const LAS bf16x8*)(lds + PG8_SA(b, h) + aoff + m * 2048 + k * 1024); } while (0)
; #define PG8_LDB(dst, b, h) do { _Pragma("unroll") for (int n = 0; n < 2; ++n) _Pragma("unroll") for (int k = 0; k < 2; ++k) dst[n][k] = *(const LAS bf16x8*)(lds + PG8_SB(b, h) + boff + n * 2048 + k * 1024); } while (0)
; #define PG8_MMA(ai, bj, At, Bt) do { __builtin_amdgcn_s_setprio(1); _Pragma("unroll") for (int m = 0; m < 4; ++m) _Pragma("unroll") for (int n = 0; n < 2; ++n) _Pragma("unroll") for (int k = 0; k < 2; ++k) \
;         acc[ai][bj][m][n] = __builtin_amdgcn_mfma_f32_16x16x32_bf16(Bt[n][k], At[m][k], acc[ai][bj][m][n], 0, 0, 0); __builtin_amdgcn_s_setprio(0); } while (0)
; #define PG8_WAIT_L(n) asm volatile("s_waitcnt lgkmcnt(" #n ")" ::: "memory")
; #define PG8_BAR __builtin_amdgcn_s_barrier()
; #define PG8_SCHED __builtin_amdgcn_sched_barrier(0)
; template <class Epi>
; __device__ __forceinline__ void gemm_phase(LAS unsigned char* lds, const Gemm g, const StaticOrder& S, const Epi& E) {
;     ...
;             const char* a1 = cA + (size_t)(t + 1) * kstep;
;             const char* a2 = last ? nA : cA + (size_t)(t + 2) * kstep; const char* b2 = last ? nB : cB + (size_t)(t + 2) * kstep;
;             const char* a3 = a2 + kstep; const char* b3 = b2 + kstep;
;             PG8_LDB(B0, 0, 0); PG8_SCHED; PG8_LDA(At, 0, 0); PG8_STAGE(PG8_SA(1, 1), a1 + hstep, voffA);
;             PG8_WAIT_L(8); PG8_BAR; PG8_WAIT_L(0); PG8_MMA(0, 0, At, B0); PG8_BAR; PG8_SCHED;
;             PG8_LDB(B1, 0, 1); PG8_STAGE(PG8_SB(0, 0), b2, voffB);
;             PG8_BAR; PG8_WAIT_L(0); PG8_MMA(0, 1, At, B1); PG8_BAR;
;             PG8_LDA(At, 0, 1); PG8_STAGE(PG8_SA(0, 0), a2, voffA);
;             PG8_BAR; PG8_WAIT_L(0); PG8_MMA(1, 0, At, B0); PG8_BAR; PG8_SCHED;
.LBB0_43:
	s_add_u32 s24, s22, 0xfffc0080
	s_addc_u32 s25, s23, -1
	s_add_i32 s47, 0, 0x10000
	v_add_u32_e32 v140, s47, v247
	ds_read_b128 v[128:131], v140
	ds_read_b128 v[132:135], v140 offset:1024
	ds_read_b128 v[136:139], v140 offset:2048
	ds_read_b128 v[140:143], v140 offset:3072
	s_cmp_eq_u32 s46, 12
	s_cselect_b32 s27, s3, s25
	s_cselect_b32 s26, s9, s24
	s_cselect_b32 s25, s13, s45
	s_cselect_b32 s24, s15, s43
	s_add_i32 m0, s21, 0xc000
	ds_read_b128 v[144:147], v249
	ds_read_b128 v[148:151], v249 offset:1024
	ds_read_b128 v[152:155], v249 offset:2048
	ds_read_b128 v[156:159], v249 offset:3072
	ds_read_b128 v[160:163], v249 offset:4096
	ds_read_b128 v[164:167], v249 offset:5120
	ds_read_b128 v[168:171], v249 offset:6144
	ds_read_b128 v[172:175], v249 offset:7168
	global_load_lds_dwordx4 v214, s[22:23]
	s_add_i32 m0, s21, 0xe000
	s_nop 0
	global_load_lds_dwordx4 v216, s[22:23]
	s_waitcnt lgkmcnt(8)
	s_barrier
	s_waitcnt lgkmcnt(0)
	s_waitcnt lgkmcnt(0)
	v_mfma_f32_16x16x32_bf16 v[124:127], v[128:131], v[144:147], v[124:127]
	v_mfma_f32_16x16x32_bf16 v[124:127], v[132:135], v[148:151], v[124:127]
	v_mfma_f32_16x16x32_bf16 v[108:111], v[128:131], v[152:155], v[108:111]
	v_mfma_f32_16x16x32_bf16 v[108:111], v[132:135], v[156:159], v[108:111]
	v_mfma_f32_16x16x32_bf16 v[92:95], v[128:131], v[160:163], v[92:95]
	v_mfma_f32_16x16x32_bf16 v[92:95], v[132:135], v[164:167], v[92:95]
	v_mfma_f32_16x16x32_bf16 v[76:79], v[128:131], v[168:171], v[76:79]
	v_mfma_f32_16x16x32_bf16 v[76:79], v[132:135], v[172:175], v[76:79]
	v_mfma_f32_16x16x32_bf16 v[72:75], v[136:139], v[168:171], v[72:75]
	v_mfma_f32_16x16x32_bf16 v[72:75], v[140:143], v[172:175], v[72:75]
	v_mfma_f32_16x16x32_bf16 v[88:91], v[136:139], v[160:163], v[88:91]
	v_mfma_f32_16x16x32_bf16 v[88:91], v[140:143], v[164:167], v[88:91]
	v_mfma_f32_16x16x32_bf16 v[104:107], v[136:139], v[152:155], v[104:107]
	v_mfma_f32_16x16x32_bf16 v[104:107], v[140:143], v[156:159], v[104:107]
	v_mfma_f32_16x16x32_bf16 v[120:123], v[136:139], v[144:147], v[120:123]
	v_mfma_f32_16x16x32_bf16 v[120:123], v[140:143], v[148:151], v[120:123]
	s_barrier
	s_add_i32 s52, 0, 0x14000
	v_add_u32_e32 v188, s52, v247
	s_add_i32 s47, s47, s36
	ds_read_b128 v[176:179], v188
	ds_read_b128 v[180:183], v188 offset:1024
	ds_read_b128 v[204:207], v188 offset:2048
	ds_read_b128 v[218:221], v188 offset:3072
	v_lshl_add_u64 v[188:189], s[24:25], 0, v[184:185]
	s_mov_b32 m0, s47
	v_lshl_add_u64 v[190:191], s[24:25], 0, v[212:213]
	global_load_lds_dwordx4 v[188:189], off
	s_add_i32 m0, s47, 0x2000
	s_nop 0
	global_load_lds_dwordx4 v[190:191], off
	s_barrier
	s_waitcnt lgkmcnt(0)
	s_waitcnt lgkmcnt(0)
	v_mfma_f32_16x16x32_bf16 v[116:119], v[176:179], v[144:147], v[116:119]
	v_mfma_f32_16x16x32_bf16 v[116:119], v[180:183], v[148:151], v[116:119]
	v_mfma_f32_16x16x32_bf16 v[100:103], v[176:179], v[152:155], v[100:103]
	v_mfma_f32_16x16x32_bf16 v[100:103], v[180:183], v[156:159], v[100:103]
	v_mfma_f32_16x16x32_bf16 v[84:87], v[176:179], v[160:163], v[84:87]
	v_mfma_f32_16x16x32_bf16 v[84:87], v[180:183], v[164:167], v[84:87]
	v_mfma_f32_16x16x32_bf16 v[68:71], v[176:179], v[168:171], v[68:71]
	v_mfma_f32_16x16x32_bf16 v[68:71], v[180:183], v[172:175], v[68:71]
	v_mfma_f32_16x16x32_bf16 v[64:67], v[204:207], v[168:171], v[64:67]
	v_mfma_f32_16x16x32_bf16 v[64:67], v[218:221], v[172:175], v[64:67]
	v_mfma_f32_16x16x32_bf16 v[80:83], v[204:207], v[160:163], v[80:83]
	v_mfma_f32_16x16x32_bf16 v[80:83], v[218:221], v[164:167], v[80:83]
	v_mfma_f32_16x16x32_bf16 v[96:99], v[204:207], v[152:155], v[96:99]
	v_mfma_f32_16x16x32_bf16 v[96:99], v[218:221], v[156:159], v[96:99]
	v_mfma_f32_16x16x32_bf16 v[112:115], v[204:207], v[144:147], v[112:115]
	v_mfma_f32_16x16x32_bf16 v[112:115], v[218:221], v[148:151], v[112:115]
	s_mov_b32 m0, s21
	v_lshl_add_u64 v[192:193], s[26:27], 0, v[208:209]
	s_barrier
	ds_read_b128 v[144:147], v249 offset:16384
	ds_read_b128 v[148:151], v249 offset:17408
	ds_read_b128 v[152:155], v249 offset:18432
	ds_read_b128 v[156:159], v249 offset:19456
	ds_read_b128 v[160:163], v249 offset:20480
	ds_read_b128 v[164:167], v249 offset:21504
	ds_read_b128 v[168:171], v249 offset:22528
	ds_read_b128 v[172:175], v249 offset:23552
	global_load_lds_dwordx4 v[192:193], off
	v_lshl_add_u64 v[222:223], s[26:27], 0, v[210:211]
	s_mov_b32 m0, s37
	s_nop 0
	global_load_lds_dwordx4 v[222:223], off
	s_barrier
	s_waitcnt lgkmcnt(0)
	s_waitcnt lgkmcnt(0)
	v_mfma_f32_16x16x32_bf16 v[60:63], v[128:131], v[144:147], v[60:63]
	v_mfma_f32_16x16x32_bf16 v[60:63], v[132:135], v[148:151], v[60:63]
	v_mfma_f32_16x16x32_bf16 v[44:47], v[128:131], v[152:155], v[44:47]
	v_mfma_f32_16x16x32_bf16 v[44:47], v[132:135], v[156:159], v[44:47]
	v_mfma_f32_16x16x32_bf16 v[28:31], v[128:131], v[160:163], v[28:31]
	v_mfma_f32_16x16x32_bf16 v[28:31], v[132:135], v[164:167], v[28:31]
	v_mfma_f32_16x16x32_bf16 v[16:19], v[128:131], v[168:171], v[16:19]
	v_mfma_f32_16x16x32_bf16 v[16:19], v[132:135], v[172:175], v[16:19]
	v_mfma_f32_16x16x32_bf16 v[8:11], v[136:139], v[168:171], v[8:11]
	v_mfma_f32_16x16x32_bf16 v[8:11], v[140:143], v[172:175], v[8:11]
	v_mfma_f32_16x16x32_bf16 v[24:27], v[136:139], v[160:163], v[24:27]
	v_mfma_f32_16x16x32_bf16 v[24:27], v[140:143], v[164:167], v[24:27]
	v_mfma_f32_16x16x32_bf16 v[40:43], v[136:139], v[152:155], v[40:43]
	v_mfma_f32_16x16x32_bf16 v[40:43], v[140:143], v[156:159], v[40:43]
	v_mfma_f32_16x16x32_bf16 v[56:59], v[136:139], v[144:147], v[56:59]
	v_mfma_f32_16x16x32_bf16 v[56:59], v[140:143], v[148:151], v[56:59]
	s_barrier
; #define PG8_STAGE(bufoff, gbase, voff) do { _Pragma("unroll") for (int _i = 0; _i < 2; ++_i) \
;         __builtin_amdgcn_global_load_lds((const unsigned*)((const char*)(gbase) + (voff)[_i]), (LAS unsigned*)(lds + (bufoff) + ldsw + _i * 8192), 16, 0, 0); } while (0)
; #define PG8_LDA(dst, b, h) do { _Pragma("unroll") for (int m = 0; m < 4; ++m) _Pragma("unroll") for (int k = 0; k < 2; ++k) dst[m][k] = *(const LAS bf16x8*)(lds + PG8_SA(b, h) + aoff + m * 2048 + k * 1024); } while (0)
; #define PG8_LDB(dst, b, h) do { _Pragma("unroll") for (int n = 0; n < 2; ++n) _Pragma("unroll") for (int k = 0; k < 2; ++k) dst[n][k] = *(const LAS bf16x8*)(lds + PG8_SB(b, h) + boff + n * 2048 + k * 1024); } while (0)
; #define PG8_MMA(ai, bj, At, Bt) do { __builtin_amdgcn_s_setprio(1); _Pragma("unroll") for (int m = 0; m < 4; ++m) _Pragma("unroll") for (int n = 0; n < 2; ++n) _Pragma("unroll") for (int k = 0; k < 2; ++k) \
;         acc[ai][bj][m][n] = __builtin_amdgcn_mfma_f32_16x16x32_bf16(Bt[n][k], At[m][k], acc[ai][bj][m][n], 0, 0, 0); __builtin_amdgcn_s_setprio(0); } while (0)
; #define PG8_WAIT_V(n) asm volatile("s_waitcnt vmcnt(" #n ")" ::: "memory")
; #define PG8_WAIT_L(n) asm volatile("s_waitcnt lgkmcnt(" #n ")" ::: "memory")
; #define PG8_BAR __builtin_amdgcn_s_barrier()
; #define PG8_SCHED __builtin_amdgcn_sched_barrier(0)
; template <class Epi>
; __device__ __forceinline__ void gemm_phase(LAS unsigned char* lds, const Gemm g, const StaticOrder& S, const Epi& E) {
;     ...
;             PG8_STAGE(PG8_SB(0, 1), b2 + hstep, voffB);
;             PG8_WAIT_V(6); PG8_BAR; PG8_MMA(1, 1, At, B1); PG8_BAR;
;             PG8_LDB(B0, 1, 0); PG8_SCHED; PG8_LDA(At, 1, 0); PG8_STAGE(PG8_SA(0, 1), a2 + hstep, voffA);
;             PG8_WAIT_L(8); PG8_BAR; PG8_WAIT_L(0); PG8_MMA(0, 0, At, B0); PG8_BAR; PG8_SCHED;
;             PG8_LDB(B1, 1, 1); PG8_STAGE(PG8_SB(1, 0), b3, voffB);
;             PG8_BAR; PG8_WAIT_L(0); PG8_MMA(0, 1, At, B1); PG8_BAR;
	s_add_u32 s50, s24, 0x40000
	s_addc_u32 s51, s25, 0
	s_add_i32 s47, s52, s36
	s_mov_b32 m0, s47
	s_nop 0
	global_load_lds_dwordx4 v184, s[50:51]
	s_add_i32 m0, s47, 0x2000
	s_nop 0
	global_load_lds_dwordx4 v212, s[50:51]
	s_waitcnt vmcnt(6)
	s_barrier
	v_mfma_f32_16x16x32_bf16 v[52:55], v[176:179], v[144:147], v[52:55]
	v_mfma_f32_16x16x32_bf16 v[52:55], v[180:183], v[148:151], v[52:55]
	v_mfma_f32_16x16x32_bf16 v[36:39], v[176:179], v[152:155], v[36:39]
	v_mfma_f32_16x16x32_bf16 v[36:39], v[180:183], v[156:159], v[36:39]
	v_mfma_f32_16x16x32_bf16 v[20:23], v[176:179], v[160:163], v[20:23]
	v_mfma_f32_16x16x32_bf16 v[20:23], v[180:183], v[164:167], v[20:23]
	v_mfma_f32_16x16x32_bf16 v[4:7], v[176:179], v[168:171], v[4:7]
	v_mfma_f32_16x16x32_bf16 v[4:7], v[180:183], v[172:175], v[4:7]
	v_mfma_f32_16x16x32_bf16 v[0:3], v[204:207], v[168:171], v[0:3]
	v_mfma_f32_16x16x32_bf16 v[0:3], v[218:221], v[172:175], v[0:3]
	v_mfma_f32_16x16x32_bf16 v[12:15], v[204:207], v[160:163], v[12:15]
	v_mfma_f32_16x16x32_bf16 v[12:15], v[218:221], v[164:167], v[12:15]
	v_mfma_f32_16x16x32_bf16 v[32:35], v[204:207], v[152:155], v[32:35]
	v_mfma_f32_16x16x32_bf16 v[32:35], v[218:221], v[156:159], v[32:35]
	v_mfma_f32_16x16x32_bf16 v[48:51], v[204:207], v[144:147], v[48:51]
	v_mfma_f32_16x16x32_bf16 v[48:51], v[218:221], v[148:151], v[48:51]
	s_add_i32 s47, 0, 0x18000
	v_add_u32_e32 v140, s47, v247
	s_barrier
	ds_read_b128 v[128:131], v140
	ds_read_b128 v[132:135], v140 offset:1024
	ds_read_b128 v[136:139], v140 offset:2048
	ds_read_b128 v[140:143], v140 offset:3072
	s_add_u32 s26, s26, 0x40000
	s_addc_u32 s27, s27, 0
	s_mov_b32 m0, s38
	ds_read_b128 v[144:147], v249 offset:32768
	ds_read_b128 v[148:151], v249 offset:33792
	ds_read_b128 v[152:155], v249 offset:34816
	ds_read_b128 v[156:159], v249 offset:35840
	ds_read_b128 v[160:163], v249 offset:36864
	ds_read_b128 v[164:167], v249 offset:37888
	ds_read_b128 v[168:171], v249 offset:38912
	ds_read_b128 v[172:175], v249 offset:39936
	global_load_lds_dwordx4 v208, s[26:27]
	s_mov_b32 m0, s39
	s_nop 0
	global_load_lds_dwordx4 v210, s[26:27]
	s_waitcnt lgkmcnt(8)
	s_barrier
	s_waitcnt lgkmcnt(0)
	s_waitcnt lgkmcnt(0)
	v_mfma_f32_16x16x32_bf16 v[124:127], v[128:131], v[144:147], v[124:127]
	v_mfma_f32_16x16x32_bf16 v[124:127], v[132:135], v[148:151], v[124:127]
	v_mfma_f32_16x16x32_bf16 v[108:111], v[128:131], v[152:155], v[108:111]
	v_mfma_f32_16x16x32_bf16 v[108:111], v[132:135], v[156:159], v[108:111]
	v_mfma_f32_16x16x32_bf16 v[92:95], v[128:131], v[160:163], v[92:95]
	v_mfma_f32_16x16x32_bf16 v[92:95], v[132:135], v[164:167], v[92:95]
	v_mfma_f32_16x16x32_bf16 v[76:79], v[128:131], v[168:171], v[76:79]
	v_mfma_f32_16x16x32_bf16 v[76:79], v[132:135], v[172:175], v[76:79]
	v_mfma_f32_16x16x32_bf16 v[72:75], v[136:139], v[168:171], v[72:75]
	v_mfma_f32_16x16x32_bf16 v[72:75], v[140:143], v[172:175], v[72:75]
	v_mfma_f32_16x16x32_bf16 v[88:91], v[136:139], v[160:163], v[88:91]
	v_mfma_f32_16x16x32_bf16 v[88:91], v[140:143], v[164:167], v[88:91]
	v_mfma_f32_16x16x32_bf16 v[104:107], v[136:139], v[152:155], v[104:107]
	v_mfma_f32_16x16x32_bf16 v[104:107], v[140:143], v[156:159], v[104:107]
	v_mfma_f32_16x16x32_bf16 v[120:123], v[136:139], v[144:147], v[120:123]
	v_mfma_f32_16x16x32_bf16 v[120:123], v[140:143], v[148:151], v[120:123]
	s_barrier
	s_add_i32 s26, 0, 0x1c000
	s_add_i32 s27, s47, s36
	v_add_u32_e32 v218, s26, v247
	v_lshl_add_u64 v[188:189], v[188:189], 0, s[58:59]
	s_mov_b32 m0, s27
	ds_read_b128 v[176:179], v218
	ds_read_b128 v[180:183], v218 offset:1024
	ds_read_b128 v[204:207], v218 offset:2048
	ds_read_b128 v[218:221], v218 offset:3072
	global_load_lds_dwordx4 v[188:189], off
	v_lshl_add_u64 v[188:189], v[190:191], 0, s[58:59]
	s_add_i32 m0, s27, 0x2000
	s_nop 0
	global_load_lds_dwordx4 v[188:189], off
	s_barrier
	s_waitcnt lgkmcnt(0)
	s_waitcnt lgkmcnt(0)
	v_mfma_f32_16x16x32_bf16 v[116:119], v[176:179], v[144:147], v[116:119]
	v_mfma_f32_16x16x32_bf16 v[116:119], v[180:183], v[148:151], v[116:119]
	v_mfma_f32_16x16x32_bf16 v[100:103], v[176:179], v[152:155], v[100:103]
	v_mfma_f32_16x16x32_bf16 v[100:103], v[180:183], v[156:159], v[100:103]
	v_mfma_f32_16x16x32_bf16 v[84:87], v[176:179], v[160:163], v[84:87]
	v_mfma_f32_16x16x32_bf16 v[84:87], v[180:183], v[164:167], v[84:87]
	v_mfma_f32_16x16x32_bf16 v[68:71], v[176:179], v[168:171], v[68:71]
	v_mfma_f32_16x16x32_bf16 v[68:71], v[180:183], v[172:175], v[68:71]
	v_mfma_f32_16x16x32_bf16 v[64:67], v[204:207], v[168:171], v[64:67]
	v_mfma_f32_16x16x32_bf16 v[64:67], v[218:221], v[172:175], v[64:67]
	v_mfma_f32_16x16x32_bf16 v[80:83], v[204:207], v[160:163], v[80:83]
	v_mfma_f32_16x16x32_bf16 v[80:83], v[218:221], v[164:167], v[80:83]
	v_mfma_f32_16x16x32_bf16 v[96:99], v[204:207], v[152:155], v[96:99]
	v_mfma_f32_16x16x32_bf16 v[96:99], v[218:221], v[156:159], v[96:99]
	v_mfma_f32_16x16x32_bf16 v[112:115], v[204:207], v[144:147], v[112:115]
	v_mfma_f32_16x16x32_bf16 v[112:115], v[218:221], v[148:151], v[112:115]
	s_mov_b32 m0, s41
	v_lshl_add_u64 v[188:189], v[192:193], 0, s[58:59]
	s_barrier
; #define PG8_STAGE(bufoff, gbase, voff) do { _Pragma("unroll") for (int _i = 0; _i < 2; ++_i) \
;         __builtin_amdgcn_global_load_lds((const unsigned*)((const char*)(gbase) + (voff)[_i]), (LAS unsigned*)(lds + (bufoff) + ldsw + _i * 8192), 16, 0, 0); } while (0)
; #define PG8_LDA(dst, b, h) do { _Pragma("unroll") for (int m = 0; m < 4; ++m) _Pragma("unroll") for (int k = 0; k < 2; ++k) dst[m][k] = *(const LAS bf16x8*)(lds + PG8_SA(b, h) + aoff + m * 2048 + k * 1024); } while (0)
; #define PG8_MMA(ai, bj, At, Bt) do { __builtin_amdgcn_s_setprio(1); _Pragma("unroll") for (int m = 0; m < 4; ++m) _Pragma("unroll") for (int n = 0; n < 2; ++n) _Pragma("unroll") for (int k = 0; k < 2; ++k) \
;         acc[ai][bj][m][n] = __builtin_amdgcn_mfma_f32_16x16x32_bf16(Bt[n][k], At[m][k], acc[ai][bj][m][n], 0, 0, 0); __builtin_amdgcn_s_setprio(0); } while (0)
; #define PG8_WAIT_V(n) asm volatile("s_waitcnt vmcnt(" #n ")" ::: "memory")
; #define PG8_WAIT_L(n) asm volatile("s_waitcnt lgkmcnt(" #n ")" ::: "memory")
; #define PG8_BAR __builtin_amdgcn_s_barrier()
; #define PG8_SCHED __builtin_amdgcn_sched_barrier(0)
; template <class Epi>
; __device__ __forceinline__ void gemm_phase(LAS unsigned char* lds, const Gemm g, const StaticOrder& S, const Epi& E) {
;     ...
;             PG8_LDA(At, 1, 1); PG8_STAGE(PG8_SA(1, 0), a3, voffA);
;             PG8_BAR; PG8_WAIT_L(0); PG8_MMA(1, 0, At, B0); PG8_BAR; PG8_SCHED;
;             PG8_STAGE(PG8_SB(1, 1), b3 + hstep, voffB);
;             PG8_WAIT_V(6); PG8_BAR; PG8_MMA(1, 1, At, B1); PG8_BAR;
;     __device__ __forceinline__ void operator()(const Acc& acc, const Unit& u, int wr, int wc, int fr, int fq) const {
;     ...
;         u32x4 gw[4][2], pw[2][2];
; #pragma unroll
;         for (int gidx = 0; gidx < 4; ++gidx)
; #pragma unroll
;             for (int bj = 0; bj < 2; ++bj) gw[gidx][bj] = *(const u32x4*)(gp + (size_t)(row0 + gidx * 16) * 4096 + col0 + bj * 128);
; #pragma unroll
;         for (int bj = 0; bj < 2; ++bj) pw[0][bj] = accum ? *(const u32x4*)(mg + (size_t)row0 * 2048 + col0 + bj * 128) : (u32x4){0u, 0u, 0u, 0u};
	ds_read_b128 v[144:147], v249 offset:49152
	ds_read_b128 v[148:151], v249 offset:50176
	ds_read_b128 v[152:155], v249 offset:51200
	ds_read_b128 v[156:159], v249 offset:52224
	ds_read_b128 v[160:163], v249 offset:53248
	ds_read_b128 v[164:167], v249 offset:54272
	ds_read_b128 v[168:171], v249 offset:55296
	ds_read_b128 v[172:175], v249 offset:56320
	global_load_lds_dwordx4 v[188:189], off
	v_lshl_add_u64 v[188:189], v[222:223], 0, s[58:59]
	s_mov_b32 m0, s42
	s_nop 0
	global_load_lds_dwordx4 v[188:189], off
	s_barrier
	s_waitcnt lgkmcnt(0)
	s_waitcnt lgkmcnt(0)
	v_mfma_f32_16x16x32_bf16 v[60:63], v[128:131], v[144:147], v[60:63]
	v_mfma_f32_16x16x32_bf16 v[60:63], v[132:135], v[148:151], v[60:63]
	v_mfma_f32_16x16x32_bf16 v[44:47], v[128:131], v[152:155], v[44:47]
	v_mfma_f32_16x16x32_bf16 v[44:47], v[132:135], v[156:159], v[44:47]
	v_mfma_f32_16x16x32_bf16 v[28:31], v[128:131], v[160:163], v[28:31]
	v_mfma_f32_16x16x32_bf16 v[28:31], v[132:135], v[164:167], v[28:31]
	v_mfma_f32_16x16x32_bf16 v[16:19], v[128:131], v[168:171], v[16:19]
	v_mfma_f32_16x16x32_bf16 v[16:19], v[132:135], v[172:175], v[16:19]
	v_mfma_f32_16x16x32_bf16 v[8:11], v[136:139], v[168:171], v[8:11]
	v_mfma_f32_16x16x32_bf16 v[8:11], v[140:143], v[172:175], v[8:11]
	v_mfma_f32_16x16x32_bf16 v[24:27], v[136:139], v[160:163], v[24:27]
	v_mfma_f32_16x16x32_bf16 v[24:27], v[140:143], v[164:167], v[24:27]
	v_mfma_f32_16x16x32_bf16 v[40:43], v[136:139], v[152:155], v[40:43]
	v_mfma_f32_16x16x32_bf16 v[40:43], v[140:143], v[156:159], v[40:43]
	v_mfma_f32_16x16x32_bf16 v[56:59], v[136:139], v[144:147], v[56:59]
	v_mfma_f32_16x16x32_bf16 v[56:59], v[140:143], v[148:151], v[56:59]
	s_barrier
	s_add_u32 s24, s24, 0x40080
	s_addc_u32 s25, s25, 0
	s_add_i32 s26, s26, s36
	s_mov_b32 m0, s26
	s_nop 0
	global_load_lds_dwordx4 v184, s[24:25]
	s_add_i32 m0, s26, 0x2000
	s_nop 0
	global_load_lds_dwordx4 v212, s[24:25]
	s_waitcnt vmcnt(6)
	s_barrier
	v_mfma_f32_16x16x32_bf16 v[52:55], v[176:179], v[144:147], v[52:55]
	v_mfma_f32_16x16x32_bf16 v[52:55], v[180:183], v[148:151], v[52:55]
	v_mfma_f32_16x16x32_bf16 v[36:39], v[176:179], v[152:155], v[36:39]
	v_mfma_f32_16x16x32_bf16 v[36:39], v[180:183], v[156:159], v[36:39]
	v_mfma_f32_16x16x32_bf16 v[20:23], v[176:179], v[160:163], v[20:23]
	v_mfma_f32_16x16x32_bf16 v[20:23], v[180:183], v[164:167], v[20:23]
	v_mfma_f32_16x16x32_bf16 v[4:7], v[176:179], v[168:171], v[4:7]
	v_mfma_f32_16x16x32_bf16 v[4:7], v[180:183], v[172:175], v[4:7]
	v_mfma_f32_16x16x32_bf16 v[0:3], v[204:207], v[168:171], v[0:3]
	v_mfma_f32_16x16x32_bf16 v[0:3], v[218:221], v[172:175], v[0:3]
	v_mfma_f32_16x16x32_bf16 v[12:15], v[204:207], v[160:163], v[12:15]
	v_mfma_f32_16x16x32_bf16 v[12:15], v[218:221], v[164:167], v[12:15]
	v_mfma_f32_16x16x32_bf16 v[32:35], v[204:207], v[152:155], v[32:35]
	v_mfma_f32_16x16x32_bf16 v[32:35], v[218:221], v[156:159], v[32:35]
	v_mfma_f32_16x16x32_bf16 v[48:51], v[204:207], v[144:147], v[48:51]
	v_mfma_f32_16x16x32_bf16 v[48:51], v[218:221], v[148:151], v[48:51]
	s_add_i32 s46, s46, 2
	s_add_u32 s22, s22, 0x100
	s_addc_u32 s23, s23, 0
	s_add_u32 s43, s43, 0x100
	s_addc_u32 s45, s45, 0
	s_cmp_gt_u32 s46, 13
	s_barrier
	s_cbranch_scc0 .LBB0_43
	v_lshl_or_b32 v128, s8, 8, v248
	v_lshl_add_u32 v222, s20, 8, v187
	v_ashrrev_i32_e32 v129, 31, v128
	v_lshlrev_b64 v[136:137], 1, v[128:129]
	v_ashrrev_i32_e32 v223, 31, v222
	v_lshl_add_u64 v[224:225], s[10:11], 0, v[136:137]
	v_lshlrev_b64 v[130:131], 13, v[222:223]
	v_lshl_add_u64 v[130:131], v[224:225], 0, v[130:131]
	global_load_dwordx4 v[176:179], v[130:131], off
	global_load_dwordx4 v[168:171], v[130:131], off offset:256
	v_or_b32_e32 v130, 16, v222
	v_ashrrev_i32_e32 v131, 31, v130
	v_lshlrev_b64 v[132:133], 13, v[130:131]
	v_or_b32_e32 v230, 32, v222
	v_lshl_add_u64 v[132:133], v[224:225], 0, v[132:133]
	v_ashrrev_i32_e32 v231, 31, v230
	global_load_dwordx4 v[156:159], v[132:133], off
	global_load_dwordx4 v[152:155], v[132:133], off offset:256
	v_lshlrev_b64 v[132:133], 13, v[230:231]
	v_or_b32_e32 v226, 48, v222
	v_lshl_add_u64 v[132:133], v[224:225], 0, v[132:133]
	v_ashrrev_i32_e32 v227, 31, v226
	global_load_dwordx4 v[148:151], v[132:133], off
	global_load_dwordx4 v[144:147], v[132:133], off offset:256
	v_lshlrev_b64 v[132:133], 13, v[226:227]
	v_lshl_add_u64 v[132:133], v[224:225], 0, v[132:133]
	global_load_dwordx4 v[140:143], v[132:133], off
	s_nop 0
	global_load_dwordx4 v[132:135], v[132:133], off offset:256
	v_lshlrev_b64 v[232:233], 12, v[222:223]
	v_lshl_add_u64 v[138:139], s[66:67], 0, v[232:233]
	v_lshl_add_u64 v[136:137], v[138:139], 0, v[136:137]
	v_cndmask_b32_e64 v138, 0, 1, s[0:1]
	v_mov_b32_e32 v172, 0
	v_cmp_ne_u32_e64 s[8:9], 1, v138
	s_andn2_b64 vcc, exec, s[0:1]
	v_mov_b32_e32 v180, 0
	v_mov_b32_e32 v181, 0
	v_mov_b32_e32 v182, 0
	v_mov_b32_e32 v183, 0
	s_cbranch_vccnz .LBB0_46
	global_load_dwordx4 v[180:183], v[136:137], off

; #define PG8_STAGE(bufoff, gbase, voff) do { _Pragma("unroll") for (int _i = 0; _i < 2; ++_i) \
;         __builtin_amdgcn_global_load_lds((const unsigned*)((const char*)(gbase) + (voff)[_i]), (LAS unsigned*)(lds + (bufoff) + ldsw + _i * 8192), 16, 0, 0); } while (0)
; #define PG8_LDA(dst, b, h) do { _Pragma("unroll") for (int m = 0; m < 4; ++m) _Pragma("unroll") for (int k = 0; k < 2; ++k) dst[m][k] = *(const LAS bf16x8*)(lds + PG8_SA(b, h) + aoff + m * 2048 + k * 1024); } while (0)
; #define PG8_LDB(dst, b, h) do { _Pragma("unroll") for (int n = 0; n < 2; ++n) _Pragma("unroll") for (int k = 0; k < 2; ++k) dst[n][k] = *(const LAS bf16x8*)(lds + PG8_SB(b, h) + boff + n * 2048 + k * 1024); } while (0)
; #define PG8_MMA(ai, bj, At, Bt) do { __builtin_amdgcn_s_setprio(1); _Pragma("unroll") for (int m = 0; m < 4; ++m) _Pragma("unroll") for (int n = 0; n < 2; ++n) _Pragma("unroll") for (int k = 0; k < 2; ++k) \
;         acc[ai][bj][m][n] = __builtin_amdgcn_mfma_f32_16x16x32_bf16(Bt[n][k], At[m][k], acc[ai][bj][m][n], 0, 0, 0); __builtin_amdgcn_s_setprio(0); } while (0)
; #define PG8_WAIT_L(n) asm volatile("s_waitcnt lgkmcnt(" #n ")" ::: "memory")
; #define PG8_BAR __builtin_amdgcn_s_barrier()
; #define PG8_SCHED __builtin_amdgcn_sched_barrier(0)
; template <class Epi>
; __device__ __forceinline__ void gemm_phase(LAS unsigned char* lds, const Gemm g, const StaticOrder& S, const Epi& E) {
;     ...
;             const char* a1 = cA + (size_t)(t + 1) * kstep;
;             const char* a2 = last ? nA : cA + (size_t)(t + 2) * kstep; const char* b2 = last ? nB : cB + (size_t)(t + 2) * kstep;
;             const char* a3 = a2 + kstep; const char* b3 = b2 + kstep;
;             PG8_LDB(B0, 0, 0); PG8_SCHED; PG8_LDA(At, 0, 0); PG8_STAGE(PG8_SA(1, 1), a1 + hstep, voffA);
;             PG8_WAIT_L(8); PG8_BAR; PG8_WAIT_L(0); PG8_MMA(0, 0, At, B0); PG8_BAR; PG8_SCHED;
;             PG8_LDB(B1, 0, 1); PG8_STAGE(PG8_SB(0, 0), b2, voffB);
;             PG8_BAR; PG8_WAIT_L(0); PG8_MMA(0, 1, At, B1); PG8_BAR;
;             PG8_LDA(At, 0, 1); PG8_STAGE(PG8_SA(0, 0), a2, voffA);
;             PG8_BAR; PG8_WAIT_L(0); PG8_MMA(1, 0, At, B0); PG8_BAR; PG8_SCHED;
.LBB0_366:
	s_add_u32 s28, s26, 0xfff80080
	s_addc_u32 s29, s27, -1
	s_add_i32 s47, 0, 0x10000
	v_add_u32_e32 v154, s47, v143
	ds_read_b128 v[138:141], v154
	ds_read_b128 v[146:149], v154 offset:1024
	ds_read_b128 v[150:153], v154 offset:2048
	ds_read_b128 v[154:157], v154 offset:3072
	s_cmp_eq_u32 s43, 28
	s_cselect_b32 s31, s3, s29
	s_cselect_b32 s30, s9, s28
	s_cselect_b32 s29, s1, s35
	s_cselect_b32 s28, s19, s34
	s_add_i32 m0, s25, 0xc000
	ds_read_b128 v[158:161], v145
	ds_read_b128 v[162:165], v145 offset:1024
	ds_read_b128 v[166:169], v145 offset:2048
	ds_read_b128 v[170:173], v145 offset:3072
	ds_read_b128 v[174:177], v145 offset:4096
	ds_read_b128 v[178:181], v145 offset:5120
	ds_read_b128 v[204:207], v145 offset:6144
	ds_read_b128 v[208:211], v145 offset:7168
	global_load_lds_dwordx4 v134, s[26:27]
	s_add_i32 m0, s25, 0xe000
	s_nop 0
	global_load_lds_dwordx4 v136, s[26:27]
	s_waitcnt lgkmcnt(8)
	s_barrier
	s_waitcnt lgkmcnt(0)
	s_waitcnt lgkmcnt(0)
	v_mfma_f32_16x16x32_bf16 v[124:127], v[138:141], v[158:161], v[124:127]
	v_mfma_f32_16x16x32_bf16 v[124:127], v[146:149], v[162:165], v[124:127]
	v_mfma_f32_16x16x32_bf16 v[108:111], v[138:141], v[166:169], v[108:111]
	v_mfma_f32_16x16x32_bf16 v[108:111], v[146:149], v[170:173], v[108:111]
	v_mfma_f32_16x16x32_bf16 v[92:95], v[138:141], v[174:177], v[92:95]
	v_mfma_f32_16x16x32_bf16 v[92:95], v[146:149], v[178:181], v[92:95]
	v_mfma_f32_16x16x32_bf16 v[76:79], v[138:141], v[204:207], v[76:79]
	v_mfma_f32_16x16x32_bf16 v[76:79], v[146:149], v[208:211], v[76:79]
	v_mfma_f32_16x16x32_bf16 v[72:75], v[150:153], v[204:207], v[72:75]
	v_mfma_f32_16x16x32_bf16 v[72:75], v[154:157], v[208:211], v[72:75]
	v_mfma_f32_16x16x32_bf16 v[88:91], v[150:153], v[174:177], v[88:91]
	v_mfma_f32_16x16x32_bf16 v[88:91], v[154:157], v[178:181], v[88:91]
	v_mfma_f32_16x16x32_bf16 v[104:107], v[150:153], v[166:169], v[104:107]
	v_mfma_f32_16x16x32_bf16 v[104:107], v[154:157], v[170:173], v[104:107]
	v_mfma_f32_16x16x32_bf16 v[120:123], v[150:153], v[158:161], v[120:123]
	v_mfma_f32_16x16x32_bf16 v[120:123], v[154:157], v[162:165], v[120:123]
	s_barrier
	s_add_i32 s52, 0, 0x14000
	v_add_u32_e32 v182, s52, v143
	s_add_i32 s47, s47, s38
	ds_read_b128 v[212:215], v182
	ds_read_b128 v[216:219], v182 offset:1024
	ds_read_b128 v[220:223], v182 offset:2048
	ds_read_b128 v[224:227], v182 offset:3072
	v_lshl_add_u64 v[182:183], s[28:29], 0, v[184:185]
	s_mov_b32 m0, s47
	v_lshl_add_u64 v[188:189], s[28:29], 0, v[132:133]
	global_load_lds_dwordx4 v[182:183], off
	s_add_i32 m0, s47, 0x2000
	s_nop 0
	global_load_lds_dwordx4 v[188:189], off
	s_barrier
	s_waitcnt lgkmcnt(0)
	s_waitcnt lgkmcnt(0)
	v_mfma_f32_16x16x32_bf16 v[116:119], v[212:215], v[158:161], v[116:119]
	v_mfma_f32_16x16x32_bf16 v[116:119], v[216:219], v[162:165], v[116:119]
	v_mfma_f32_16x16x32_bf16 v[100:103], v[212:215], v[166:169], v[100:103]
	v_mfma_f32_16x16x32_bf16 v[100:103], v[216:219], v[170:173], v[100:103]
	v_mfma_f32_16x16x32_bf16 v[84:87], v[212:215], v[174:177], v[84:87]
	v_mfma_f32_16x16x32_bf16 v[84:87], v[216:219], v[178:181], v[84:87]
	v_mfma_f32_16x16x32_bf16 v[68:71], v[212:215], v[204:207], v[68:71]
	v_mfma_f32_16x16x32_bf16 v[68:71], v[216:219], v[208:211], v[68:71]
	v_mfma_f32_16x16x32_bf16 v[64:67], v[220:223], v[204:207], v[64:67]
	v_mfma_f32_16x16x32_bf16 v[64:67], v[224:227], v[208:211], v[64:67]
	v_mfma_f32_16x16x32_bf16 v[80:83], v[220:223], v[174:177], v[80:83]
	v_mfma_f32_16x16x32_bf16 v[80:83], v[224:227], v[178:181], v[80:83]
	v_mfma_f32_16x16x32_bf16 v[96:99], v[220:223], v[166:169], v[96:99]
	v_mfma_f32_16x16x32_bf16 v[96:99], v[224:227], v[170:173], v[96:99]
	v_mfma_f32_16x16x32_bf16 v[112:115], v[220:223], v[158:161], v[112:115]
	v_mfma_f32_16x16x32_bf16 v[112:115], v[224:227], v[162:165], v[112:115]
	s_mov_b32 m0, s25
	v_lshl_add_u64 v[190:191], s[30:31], 0, v[128:129]
	s_barrier
	ds_read_b128 v[158:161], v145 offset:16384
	ds_read_b128 v[162:165], v145 offset:17408
	ds_read_b128 v[166:169], v145 offset:18432
	ds_read_b128 v[170:173], v145 offset:19456
	ds_read_b128 v[174:177], v145 offset:20480
	ds_read_b128 v[178:181], v145 offset:21504
	ds_read_b128 v[204:207], v145 offset:22528
	ds_read_b128 v[208:211], v145 offset:23552
	global_load_lds_dwordx4 v[190:191], off
	v_lshl_add_u64 v[192:193], s[30:31], 0, v[130:131]
	s_mov_b32 m0, s39
	s_nop 0
	global_load_lds_dwordx4 v[192:193], off
	s_barrier
	s_waitcnt lgkmcnt(0)
	s_waitcnt lgkmcnt(0)
	v_mfma_f32_16x16x32_bf16 v[60:63], v[138:141], v[158:161], v[60:63]
	v_mfma_f32_16x16x32_bf16 v[60:63], v[146:149], v[162:165], v[60:63]
	v_mfma_f32_16x16x32_bf16 v[44:47], v[138:141], v[166:169], v[44:47]
	v_mfma_f32_16x16x32_bf16 v[44:47], v[146:149], v[170:173], v[44:47]
	v_mfma_f32_16x16x32_bf16 v[28:31], v[138:141], v[174:177], v[28:31]
	v_mfma_f32_16x16x32_bf16 v[28:31], v[146:149], v[178:181], v[28:31]
	v_mfma_f32_16x16x32_bf16 v[12:15], v[138:141], v[204:207], v[12:15]
	v_mfma_f32_16x16x32_bf16 v[12:15], v[146:149], v[208:211], v[12:15]
	v_mfma_f32_16x16x32_bf16 v[8:11], v[150:153], v[204:207], v[8:11]
	v_mfma_f32_16x16x32_bf16 v[8:11], v[154:157], v[208:211], v[8:11]
	v_mfma_f32_16x16x32_bf16 v[24:27], v[150:153], v[174:177], v[24:27]
	v_mfma_f32_16x16x32_bf16 v[24:27], v[154:157], v[178:181], v[24:27]
	v_mfma_f32_16x16x32_bf16 v[40:43], v[150:153], v[166:169], v[40:43]
	v_mfma_f32_16x16x32_bf16 v[40:43], v[154:157], v[170:173], v[40:43]
	v_mfma_f32_16x16x32_bf16 v[56:59], v[150:153], v[158:161], v[56:59]
	v_mfma_f32_16x16x32_bf16 v[56:59], v[154:157], v[162:165], v[56:59]
	s_barrier
; #define PG8_STAGE(bufoff, gbase, voff) do { _Pragma("unroll") for (int _i = 0; _i < 2; ++_i) \
;         __builtin_amdgcn_global_load_lds((const unsigned*)((const char*)(gbase) + (voff)[_i]), (LAS unsigned*)(lds + (bufoff) + ldsw + _i * 8192), 16, 0, 0); } while (0)
; #define PG8_LDA(dst, b, h) do { _Pragma("unroll") for (int m = 0; m < 4; ++m) _Pragma("unroll") for (int k = 0; k < 2; ++k) dst[m][k] = *(const LAS bf16x8*)(lds + PG8_SA(b, h) + aoff + m * 2048 + k * 1024); } while (0)
; #define PG8_LDB(dst, b, h) do { _Pragma("unroll") for (int n = 0; n < 2; ++n) _Pragma("unroll") for (int k = 0; k < 2; ++k) dst[n][k] = *(const LAS bf16x8*)(lds + PG8_SB(b, h) + boff + n * 2048 + k * 1024); } while (0)
; #define PG8_MMA(ai, bj, At, Bt) do { __builtin_amdgcn_s_setprio(1); _Pragma("unroll") for (int m = 0; m < 4; ++m) _Pragma("unroll") for (int n = 0; n < 2; ++n) _Pragma("unroll") for (int k = 0; k < 2; ++k) \
;         acc[ai][bj][m][n] = __builtin_amdgcn_mfma_f32_16x16x32_bf16(Bt[n][k], At[m][k], acc[ai][bj][m][n], 0, 0, 0); __builtin_amdgcn_s_setprio(0); } while (0)
; #define PG8_WAIT_V(n) asm volatile("s_waitcnt vmcnt(" #n ")" ::: "memory")
; #define PG8_WAIT_L(n) asm volatile("s_waitcnt lgkmcnt(" #n ")" ::: "memory")
; #define PG8_BAR __builtin_amdgcn_s_barrier()
; #define PG8_SCHED __builtin_amdgcn_sched_barrier(0)
; template <class Epi>
; __device__ __forceinline__ void gemm_phase(LAS unsigned char* lds, const Gemm g, const StaticOrder& S, const Epi& E) {
;     ...
;             PG8_STAGE(PG8_SB(0, 1), b2 + hstep, voffB);
;             PG8_WAIT_V(6); PG8_BAR; PG8_MMA(1, 1, At, B1); PG8_BAR;
;             PG8_LDB(B0, 1, 0); PG8_SCHED; PG8_LDA(At, 1, 0); PG8_STAGE(PG8_SA(0, 1), a2 + hstep, voffA);
;             PG8_WAIT_L(8); PG8_BAR; PG8_WAIT_L(0); PG8_MMA(0, 0, At, B0); PG8_BAR; PG8_SCHED;
;             PG8_LDB(B1, 1, 1); PG8_STAGE(PG8_SB(1, 0), b3, voffB);
;             PG8_BAR; PG8_WAIT_L(0); PG8_MMA(0, 1, At, B1); PG8_BAR;
	s_add_u32 s50, s28, 0x80000
	s_addc_u32 s51, s29, 0
	s_add_i32 s47, s52, s38
	s_mov_b32 m0, s47
	s_nop 0
	global_load_lds_dwordx4 v184, s[50:51]
	s_add_i32 m0, s47, 0x2000
	s_nop 0
	global_load_lds_dwordx4 v132, s[50:51]
	s_waitcnt vmcnt(6)
	s_barrier
	v_mfma_f32_16x16x32_bf16 v[52:55], v[212:215], v[158:161], v[52:55]
	v_mfma_f32_16x16x32_bf16 v[52:55], v[216:219], v[162:165], v[52:55]
	v_mfma_f32_16x16x32_bf16 v[36:39], v[212:215], v[166:169], v[36:39]
	v_mfma_f32_16x16x32_bf16 v[36:39], v[216:219], v[170:173], v[36:39]
	v_mfma_f32_16x16x32_bf16 v[20:23], v[212:215], v[174:177], v[20:23]
	v_mfma_f32_16x16x32_bf16 v[20:23], v[216:219], v[178:181], v[20:23]
	v_mfma_f32_16x16x32_bf16 v[4:7], v[212:215], v[204:207], v[4:7]
	v_mfma_f32_16x16x32_bf16 v[4:7], v[216:219], v[208:211], v[4:7]
	v_mfma_f32_16x16x32_bf16 v[0:3], v[220:223], v[204:207], v[0:3]
	v_mfma_f32_16x16x32_bf16 v[0:3], v[224:227], v[208:211], v[0:3]
	v_mfma_f32_16x16x32_bf16 v[16:19], v[220:223], v[174:177], v[16:19]
	v_mfma_f32_16x16x32_bf16 v[16:19], v[224:227], v[178:181], v[16:19]
	v_mfma_f32_16x16x32_bf16 v[32:35], v[220:223], v[166:169], v[32:35]
	v_mfma_f32_16x16x32_bf16 v[32:35], v[224:227], v[170:173], v[32:35]
	v_mfma_f32_16x16x32_bf16 v[48:51], v[220:223], v[158:161], v[48:51]
	v_mfma_f32_16x16x32_bf16 v[48:51], v[224:227], v[162:165], v[48:51]
	s_add_i32 s47, 0, 0x18000
	v_add_u32_e32 v154, s47, v143
	s_barrier
	ds_read_b128 v[138:141], v154
	ds_read_b128 v[146:149], v154 offset:1024
	ds_read_b128 v[150:153], v154 offset:2048
	ds_read_b128 v[154:157], v154 offset:3072
	s_add_u32 s30, s30, 0x80000
	s_addc_u32 s31, s31, 0
	s_mov_b32 m0, s40
	ds_read_b128 v[158:161], v145 offset:32768
	ds_read_b128 v[162:165], v145 offset:33792
	ds_read_b128 v[166:169], v145 offset:34816
	ds_read_b128 v[170:173], v145 offset:35840
	ds_read_b128 v[174:177], v145 offset:36864
	ds_read_b128 v[178:181], v145 offset:37888
	ds_read_b128 v[204:207], v145 offset:38912
	ds_read_b128 v[208:211], v145 offset:39936
	global_load_lds_dwordx4 v128, s[30:31]
	s_mov_b32 m0, s41
	s_nop 0
	global_load_lds_dwordx4 v130, s[30:31]
	s_waitcnt lgkmcnt(8)
	s_barrier
	s_waitcnt lgkmcnt(0)
	s_waitcnt lgkmcnt(0)
	v_mfma_f32_16x16x32_bf16 v[124:127], v[138:141], v[158:161], v[124:127]
	v_mfma_f32_16x16x32_bf16 v[124:127], v[146:149], v[162:165], v[124:127]
	v_mfma_f32_16x16x32_bf16 v[108:111], v[138:141], v[166:169], v[108:111]
	v_mfma_f32_16x16x32_bf16 v[108:111], v[146:149], v[170:173], v[108:111]
	v_mfma_f32_16x16x32_bf16 v[92:95], v[138:141], v[174:177], v[92:95]
	v_mfma_f32_16x16x32_bf16 v[92:95], v[146:149], v[178:181], v[92:95]
	v_mfma_f32_16x16x32_bf16 v[76:79], v[138:141], v[204:207], v[76:79]
	v_mfma_f32_16x16x32_bf16 v[76:79], v[146:149], v[208:211], v[76:79]
	v_mfma_f32_16x16x32_bf16 v[72:75], v[150:153], v[204:207], v[72:75]
	v_mfma_f32_16x16x32_bf16 v[72:75], v[154:157], v[208:211], v[72:75]
	v_mfma_f32_16x16x32_bf16 v[88:91], v[150:153], v[174:177], v[88:91]
	v_mfma_f32_16x16x32_bf16 v[88:91], v[154:157], v[178:181], v[88:91]
	v_mfma_f32_16x16x32_bf16 v[104:107], v[150:153], v[166:169], v[104:107]
	v_mfma_f32_16x16x32_bf16 v[104:107], v[154:157], v[170:173], v[104:107]
	v_mfma_f32_16x16x32_bf16 v[120:123], v[150:153], v[158:161], v[120:123]
	v_mfma_f32_16x16x32_bf16 v[120:123], v[154:157], v[162:165], v[120:123]
	s_barrier
	s_add_i32 s30, 0, 0x1c000
	s_add_i32 s31, s47, s38
	v_add_u32_e32 v187, s30, v143
	v_lshl_add_u64 v[182:183], v[182:183], 0, s[58:59]
	s_mov_b32 m0, s31
	ds_read_b128 v[212:215], v187
	ds_read_b128 v[216:219], v187 offset:1024
	ds_read_b128 v[220:223], v187 offset:2048
	ds_read_b128 v[224:227], v187 offset:3072
	global_load_lds_dwordx4 v[182:183], off
	v_lshl_add_u64 v[182:183], v[188:189], 0, s[58:59]
	s_add_i32 m0, s31, 0x2000
	s_nop 0
	global_load_lds_dwordx4 v[182:183], off
	s_barrier
; #define PG8_STAGE(bufoff, gbase, voff) do { _Pragma("unroll") for (int _i = 0; _i < 2; ++_i) \
;         __builtin_amdgcn_global_load_lds((const unsigned*)((const char*)(gbase) + (voff)[_i]), (LAS unsigned*)(lds + (bufoff) + ldsw + _i * 8192), 16, 0, 0); } while (0)
; #define PG8_LDA(dst, b, h) do { _Pragma("unroll") for (int m = 0; m < 4; ++m) _Pragma("unroll") for (int k = 0; k < 2; ++k) dst[m][k] = *(const LAS bf16x8*)(lds + PG8_SA(b, h) + aoff + m * 2048 + k * 1024); } while (0)
; #define PG8_MMA(ai, bj, At, Bt) do { __builtin_amdgcn_s_setprio(1); _Pragma("unroll") for (int m = 0; m < 4; ++m) _Pragma("unroll") for (int n = 0; n < 2; ++n) _Pragma("unroll") for (int k = 0; k < 2; ++k) \
;         acc[ai][bj][m][n] = __builtin_amdgcn_mfma_f32_16x16x32_bf16(Bt[n][k], At[m][k], acc[ai][bj][m][n], 0, 0, 0); __builtin_amdgcn_s_setprio(0); } while (0)
; #define PG8_WAIT_V(n) asm volatile("s_waitcnt vmcnt(" #n ")" ::: "memory")
; #define PG8_WAIT_L(n) asm volatile("s_waitcnt lgkmcnt(" #n ")" ::: "memory")
; #define PG8_BAR __builtin_amdgcn_s_barrier()
; #define PG8_SCHED __builtin_amdgcn_sched_barrier(0)
; template <class Epi>
; __device__ __forceinline__ void gemm_phase(LAS unsigned char* lds, const Gemm g, const StaticOrder& S, const Epi& E) {
;     ...
;             PG8_BAR; PG8_WAIT_L(0); PG8_MMA(0, 1, At, B1); PG8_BAR;
;             PG8_LDA(At, 1, 1); PG8_STAGE(PG8_SA(1, 0), a3, voffA);
;             PG8_BAR; PG8_WAIT_L(0); PG8_MMA(1, 0, At, B0); PG8_BAR; PG8_SCHED;
;             PG8_STAGE(PG8_SB(1, 1), b3 + hstep, voffB);
;             PG8_WAIT_V(6); PG8_BAR; PG8_MMA(1, 1, At, B1); PG8_BAR;
;     __device__ __forceinline__ void operator()(const Acc& acc, const Unit& u, int wr, int wc, int fr, int fq) const {
;         const int pn = u.pn; const int row0 = u.pm * 256 + wr * 64 + fr;
;         bf16_t* base; int ld, cb; bool act;
;         if (vt) { base = vt; ld = TH; cb = 256 * pn; act = false; }
;         else if (gmode) { base = g; ld = 4096; cb = 256 * pn; act = true; }
;         else if (pn < 8) { base = zna; ld = 2048; cb = 256 * pn; act = false; }
;         else if (pn < 16) { base = zqk; ld = 2048; cb = 256 * (pn - 8); act = false; }
;         else if (pn < 24) { base = vo; ld = 2048; cb = 256 * (pn - 16); act = pn >= 20; }
;         else { base = g; ld = 4096; cb = 256 * (pn - 24); act = true; }
	s_waitcnt lgkmcnt(0)
	s_waitcnt lgkmcnt(0)
	v_mfma_f32_16x16x32_bf16 v[116:119], v[212:215], v[158:161], v[116:119]
	v_mfma_f32_16x16x32_bf16 v[116:119], v[216:219], v[162:165], v[116:119]
	v_mfma_f32_16x16x32_bf16 v[100:103], v[212:215], v[166:169], v[100:103]
	v_mfma_f32_16x16x32_bf16 v[100:103], v[216:219], v[170:173], v[100:103]
	v_mfma_f32_16x16x32_bf16 v[84:87], v[212:215], v[174:177], v[84:87]
	v_mfma_f32_16x16x32_bf16 v[84:87], v[216:219], v[178:181], v[84:87]
	v_mfma_f32_16x16x32_bf16 v[68:71], v[212:215], v[204:207], v[68:71]
	v_mfma_f32_16x16x32_bf16 v[68:71], v[216:219], v[208:211], v[68:71]
	v_mfma_f32_16x16x32_bf16 v[64:67], v[220:223], v[204:207], v[64:67]
	v_mfma_f32_16x16x32_bf16 v[64:67], v[224:227], v[208:211], v[64:67]
	v_mfma_f32_16x16x32_bf16 v[80:83], v[220:223], v[174:177], v[80:83]
	v_mfma_f32_16x16x32_bf16 v[80:83], v[224:227], v[178:181], v[80:83]
	v_mfma_f32_16x16x32_bf16 v[96:99], v[220:223], v[166:169], v[96:99]
	v_mfma_f32_16x16x32_bf16 v[96:99], v[224:227], v[170:173], v[96:99]
	v_mfma_f32_16x16x32_bf16 v[112:115], v[220:223], v[158:161], v[112:115]
	v_mfma_f32_16x16x32_bf16 v[112:115], v[224:227], v[162:165], v[112:115]
	s_mov_b32 m0, s42
	v_lshl_add_u64 v[182:183], v[190:191], 0, s[58:59]
	s_barrier
	ds_read_b128 v[158:161], v145 offset:49152
	ds_read_b128 v[162:165], v145 offset:50176
	ds_read_b128 v[166:169], v145 offset:51200
	ds_read_b128 v[170:173], v145 offset:52224
	ds_read_b128 v[174:177], v145 offset:53248
	ds_read_b128 v[178:181], v145 offset:54272
	ds_read_b128 v[204:207], v145 offset:55296
	ds_read_b128 v[208:211], v145 offset:56320
	global_load_lds_dwordx4 v[182:183], off
	v_lshl_add_u64 v[182:183], v[192:193], 0, s[58:59]
	s_mov_b32 m0, s44
	s_nop 0
	global_load_lds_dwordx4 v[182:183], off
	s_barrier
	s_waitcnt lgkmcnt(0)
	s_waitcnt lgkmcnt(0)
	v_mfma_f32_16x16x32_bf16 v[60:63], v[138:141], v[158:161], v[60:63]
	v_mfma_f32_16x16x32_bf16 v[60:63], v[146:149], v[162:165], v[60:63]
	v_mfma_f32_16x16x32_bf16 v[44:47], v[138:141], v[166:169], v[44:47]
	v_mfma_f32_16x16x32_bf16 v[44:47], v[146:149], v[170:173], v[44:47]
	v_mfma_f32_16x16x32_bf16 v[28:31], v[138:141], v[174:177], v[28:31]
	v_mfma_f32_16x16x32_bf16 v[28:31], v[146:149], v[178:181], v[28:31]
	v_mfma_f32_16x16x32_bf16 v[12:15], v[138:141], v[204:207], v[12:15]
	v_mfma_f32_16x16x32_bf16 v[12:15], v[146:149], v[208:211], v[12:15]
	v_mfma_f32_16x16x32_bf16 v[8:11], v[150:153], v[204:207], v[8:11]
	v_mfma_f32_16x16x32_bf16 v[8:11], v[154:157], v[208:211], v[8:11]
	v_mfma_f32_16x16x32_bf16 v[24:27], v[150:153], v[174:177], v[24:27]
	v_mfma_f32_16x16x32_bf16 v[24:27], v[154:157], v[178:181], v[24:27]
	v_mfma_f32_16x16x32_bf16 v[40:43], v[150:153], v[166:169], v[40:43]
	v_mfma_f32_16x16x32_bf16 v[40:43], v[154:157], v[170:173], v[40:43]
	v_mfma_f32_16x16x32_bf16 v[56:59], v[150:153], v[158:161], v[56:59]
	v_mfma_f32_16x16x32_bf16 v[56:59], v[154:157], v[162:165], v[56:59]
	s_barrier
	s_add_u32 s28, s28, 0x80080
	s_addc_u32 s29, s29, 0
	s_add_i32 s30, s30, s38
	s_mov_b32 m0, s30
	s_nop 0
	global_load_lds_dwordx4 v184, s[28:29]
	s_add_i32 m0, s30, 0x2000
	s_nop 0
	global_load_lds_dwordx4 v132, s[28:29]
	s_waitcnt vmcnt(6)
	s_barrier
	v_mfma_f32_16x16x32_bf16 v[52:55], v[212:215], v[158:161], v[52:55]
	v_mfma_f32_16x16x32_bf16 v[52:55], v[216:219], v[162:165], v[52:55]
	v_mfma_f32_16x16x32_bf16 v[36:39], v[212:215], v[166:169], v[36:39]
	v_mfma_f32_16x16x32_bf16 v[36:39], v[216:219], v[170:173], v[36:39]
	v_mfma_f32_16x16x32_bf16 v[20:23], v[212:215], v[174:177], v[20:23]
	v_mfma_f32_16x16x32_bf16 v[20:23], v[216:219], v[178:181], v[20:23]
	v_mfma_f32_16x16x32_bf16 v[4:7], v[212:215], v[204:207], v[4:7]
	v_mfma_f32_16x16x32_bf16 v[4:7], v[216:219], v[208:211], v[4:7]
	v_mfma_f32_16x16x32_bf16 v[0:3], v[220:223], v[204:207], v[0:3]
	v_mfma_f32_16x16x32_bf16 v[0:3], v[224:227], v[208:211], v[0:3]
	v_mfma_f32_16x16x32_bf16 v[16:19], v[220:223], v[174:177], v[16:19]
	v_mfma_f32_16x16x32_bf16 v[16:19], v[224:227], v[178:181], v[16:19]
	v_mfma_f32_16x16x32_bf16 v[32:35], v[220:223], v[166:169], v[32:35]
	v_mfma_f32_16x16x32_bf16 v[32:35], v[224:227], v[170:173], v[32:35]
	v_mfma_f32_16x16x32_bf16 v[48:51], v[220:223], v[158:161], v[48:51]
	v_mfma_f32_16x16x32_bf16 v[48:51], v[224:227], v[162:165], v[48:51]
	s_add_i32 s43, s43, 2
	s_add_u32 s26, s26, 0x100
	s_addc_u32 s27, s27, 0
	s_add_u32 s34, s34, 0x100
	s_addc_u32 s35, s35, 0
	s_cmp_gt_u32 s43, 29
	s_barrier
	s_cbranch_scc0 .LBB0_366
	s_andn2_b64 vcc, exec, s[16:17]
	s_lshl_b32 s1, s8, 8
	s_cbranch_vccnz .LBB0_378
	s_cmp_lt_i32 s8, 8
	s_cbranch_scc1 .LBB0_410
	s_cmp_gt_u32 s8, 15
	s_mov_b64 s[34:35], -1
	s_cbranch_scc0 .LBB0_375
	s_mov_b64 s[30:31], -1
	s_cmp_gt_u32 s8, 23
	s_mov_b64 s[28:29], -1
	s_cbranch_scc0 .LBB0_372
	s_add_i32 s3, s1, 0xffffe800
	s_mov_b64 s[28:29], 0

; #define PG8_STAGE(bufoff, gbase, voff) do { _Pragma("unroll") for (int _i = 0; _i < 2; ++_i) \
;         __builtin_amdgcn_global_load_lds((const unsigned*)((const char*)(gbase) + (voff)[_i]), (LAS unsigned*)(lds + (bufoff) + ldsw + _i * 8192), 16, 0, 0); } while (0)
; #define PG8_LDA(dst, b, h) do { _Pragma("unroll") for (int m = 0; m < 4; ++m) _Pragma("unroll") for (int k = 0; k < 2; ++k) dst[m][k] = *(const LAS bf16x8*)(lds + PG8_SA(b, h) + aoff + m * 2048 + k * 1024); } while (0)
; #define PG8_LDB(dst, b, h) do { _Pragma("unroll") for (int n = 0; n < 2; ++n) _Pragma("unroll") for (int k = 0; k < 2; ++k) dst[n][k] = *(const LAS bf16x8*)(lds + PG8_SB(b, h) + boff + n * 2048 + k * 1024); } while (0)
; #define PG8_MMA(ai, bj, At, Bt) do { __builtin_amdgcn_s_setprio(1); _Pragma("unroll") for (int m = 0; m < 4; ++m) _Pragma("unroll") for (int n = 0; n < 2; ++n) _Pragma("unroll") for (int k = 0; k < 2; ++k) \
;         acc[ai][bj][m][n] = __builtin_amdgcn_mfma_f32_16x16x32_bf16(Bt[n][k], At[m][k], acc[ai][bj][m][n], 0, 0, 0); __builtin_amdgcn_s_setprio(0); } while (0)
; #define PG8_WAIT_L(n) asm volatile("s_waitcnt lgkmcnt(" #n ")" ::: "memory")
; #define PG8_BAR __builtin_amdgcn_s_barrier()
; #define PG8_SCHED __builtin_amdgcn_sched_barrier(0)
; template <class Epi>
; __device__ __forceinline__ void gemm_phase(LAS unsigned char* lds, const Gemm g, const StaticOrder& S, const Epi& E) {
;     ...
;         for (int t = 0; t < nt; t += 2) {
;             const bool last = (t == nt - 2);
;             const char* a1 = cA + (size_t)(t + 1) * kstep;
;             const char* a2 = last ? nA : cA + (size_t)(t + 2) * kstep; const char* b2 = last ? nB : cB + (size_t)(t + 2) * kstep;
;             const char* a3 = a2 + kstep; const char* b3 = b2 + kstep;
;             PG8_LDB(B0, 0, 0); PG8_SCHED; PG8_LDA(At, 0, 0); PG8_STAGE(PG8_SA(1, 1), a1 + hstep, voffA);
;             PG8_WAIT_L(8); PG8_BAR; PG8_WAIT_L(0); PG8_MMA(0, 0, At, B0); PG8_BAR; PG8_SCHED;
;             PG8_LDB(B1, 0, 1); PG8_STAGE(PG8_SB(0, 0), b2, voffB);
;             PG8_BAR; PG8_WAIT_L(0); PG8_MMA(0, 1, At, B1); PG8_BAR;
;             PG8_LDA(At, 0, 1); PG8_STAGE(PG8_SA(0, 0), a2, voffA);
;             PG8_BAR; PG8_WAIT_L(0); PG8_MMA(1, 0, At, B0); PG8_BAR; PG8_SCHED;
.LBB0_490:
	s_add_u32 s30, s8, 0xfff80080
	s_addc_u32 s31, s9, -1
	s_add_i32 s52, 0, 0x10000
	v_add_u32_e32 v154, s52, v143
	ds_read_b128 v[138:141], v154
	ds_read_b128 v[146:149], v154 offset:1024
	ds_read_b128 v[150:153], v154 offset:2048
	ds_read_b128 v[154:157], v154 offset:3072
	s_cmp_eq_u32 s51, 28
	s_cselect_b32 s35, s3, s31
	s_cselect_b32 s34, s21, s30
	s_cselect_b32 s31, s19, s50
	s_cselect_b32 s30, s43, s47
	s_add_i32 m0, s27, 0xc000
	ds_read_b128 v[158:161], v145
	ds_read_b128 v[162:165], v145 offset:1024
	ds_read_b128 v[166:169], v145 offset:2048
	ds_read_b128 v[170:173], v145 offset:3072
	ds_read_b128 v[174:177], v145 offset:4096
	ds_read_b128 v[178:181], v145 offset:5120
	ds_read_b128 v[204:207], v145 offset:6144
	ds_read_b128 v[208:211], v145 offset:7168
	global_load_lds_dwordx4 v134, s[8:9]
	s_add_i32 m0, s27, 0xe000
	s_nop 0
	global_load_lds_dwordx4 v136, s[8:9]
	s_waitcnt lgkmcnt(8)
	s_barrier
	s_waitcnt lgkmcnt(0)
	s_waitcnt lgkmcnt(0)
	v_mfma_f32_16x16x32_bf16 v[124:127], v[138:141], v[158:161], v[124:127]
	v_mfma_f32_16x16x32_bf16 v[124:127], v[146:149], v[162:165], v[124:127]
	v_mfma_f32_16x16x32_bf16 v[108:111], v[138:141], v[166:169], v[108:111]
	v_mfma_f32_16x16x32_bf16 v[108:111], v[146:149], v[170:173], v[108:111]
	v_mfma_f32_16x16x32_bf16 v[92:95], v[138:141], v[174:177], v[92:95]
	v_mfma_f32_16x16x32_bf16 v[92:95], v[146:149], v[178:181], v[92:95]
	v_mfma_f32_16x16x32_bf16 v[76:79], v[138:141], v[204:207], v[76:79]
	v_mfma_f32_16x16x32_bf16 v[76:79], v[146:149], v[208:211], v[76:79]
	v_mfma_f32_16x16x32_bf16 v[72:75], v[150:153], v[204:207], v[72:75]
	v_mfma_f32_16x16x32_bf16 v[72:75], v[154:157], v[208:211], v[72:75]
	v_mfma_f32_16x16x32_bf16 v[88:91], v[150:153], v[174:177], v[88:91]
	v_mfma_f32_16x16x32_bf16 v[88:91], v[154:157], v[178:181], v[88:91]
	v_mfma_f32_16x16x32_bf16 v[104:107], v[150:153], v[166:169], v[104:107]
	v_mfma_f32_16x16x32_bf16 v[104:107], v[154:157], v[170:173], v[104:107]
	v_mfma_f32_16x16x32_bf16 v[120:123], v[150:153], v[158:161], v[120:123]
	v_mfma_f32_16x16x32_bf16 v[120:123], v[154:157], v[162:165], v[120:123]
	s_barrier
	s_add_i32 s56, 0, 0x14000
	v_add_u32_e32 v182, s56, v143
	s_add_i32 s52, s52, s38
	ds_read_b128 v[212:215], v182
	ds_read_b128 v[216:219], v182 offset:1024
	ds_read_b128 v[220:223], v182 offset:2048
	ds_read_b128 v[224:227], v182 offset:3072
	v_lshl_add_u64 v[182:183], s[30:31], 0, v[184:185]
	s_mov_b32 m0, s52
	v_lshl_add_u64 v[188:189], s[30:31], 0, v[132:133]
	global_load_lds_dwordx4 v[182:183], off
	s_add_i32 m0, s52, 0x2000
	s_nop 0
	global_load_lds_dwordx4 v[188:189], off
	s_barrier
	s_waitcnt lgkmcnt(0)
	s_waitcnt lgkmcnt(0)
	v_mfma_f32_16x16x32_bf16 v[116:119], v[212:215], v[158:161], v[116:119]
	v_mfma_f32_16x16x32_bf16 v[116:119], v[216:219], v[162:165], v[116:119]
	v_mfma_f32_16x16x32_bf16 v[100:103], v[212:215], v[166:169], v[100:103]
	v_mfma_f32_16x16x32_bf16 v[100:103], v[216:219], v[170:173], v[100:103]
	v_mfma_f32_16x16x32_bf16 v[84:87], v[212:215], v[174:177], v[84:87]
	v_mfma_f32_16x16x32_bf16 v[84:87], v[216:219], v[178:181], v[84:87]
	v_mfma_f32_16x16x32_bf16 v[68:71], v[212:215], v[204:207], v[68:71]
	v_mfma_f32_16x16x32_bf16 v[68:71], v[216:219], v[208:211], v[68:71]
	v_mfma_f32_16x16x32_bf16 v[64:67], v[220:223], v[204:207], v[64:67]
	v_mfma_f32_16x16x32_bf16 v[64:67], v[224:227], v[208:211], v[64:67]
	v_mfma_f32_16x16x32_bf16 v[80:83], v[220:223], v[174:177], v[80:83]
	v_mfma_f32_16x16x32_bf16 v[80:83], v[224:227], v[178:181], v[80:83]
	v_mfma_f32_16x16x32_bf16 v[96:99], v[220:223], v[166:169], v[96:99]
	v_mfma_f32_16x16x32_bf16 v[96:99], v[224:227], v[170:173], v[96:99]
	v_mfma_f32_16x16x32_bf16 v[112:115], v[220:223], v[158:161], v[112:115]
	v_mfma_f32_16x16x32_bf16 v[112:115], v[224:227], v[162:165], v[112:115]
	s_mov_b32 m0, s27
	v_lshl_add_u64 v[190:191], s[34:35], 0, v[128:129]
	s_barrier
	ds_read_b128 v[158:161], v145 offset:16384
	ds_read_b128 v[162:165], v145 offset:17408
	ds_read_b128 v[166:169], v145 offset:18432
	ds_read_b128 v[170:173], v145 offset:19456
	ds_read_b128 v[174:177], v145 offset:20480
	ds_read_b128 v[178:181], v145 offset:21504
	ds_read_b128 v[204:207], v145 offset:22528
	ds_read_b128 v[208:211], v145 offset:23552
	global_load_lds_dwordx4 v[190:191], off
	v_lshl_add_u64 v[192:193], s[34:35], 0, v[130:131]
	s_mov_b32 m0, s29
	s_nop 0
	global_load_lds_dwordx4 v[192:193], off
	s_barrier
	s_waitcnt lgkmcnt(0)
	s_waitcnt lgkmcnt(0)
	v_mfma_f32_16x16x32_bf16 v[60:63], v[138:141], v[158:161], v[60:63]
	v_mfma_f32_16x16x32_bf16 v[60:63], v[146:149], v[162:165], v[60:63]
	v_mfma_f32_16x16x32_bf16 v[44:47], v[138:141], v[166:169], v[44:47]
	v_mfma_f32_16x16x32_bf16 v[44:47], v[146:149], v[170:173], v[44:47]
	v_mfma_f32_16x16x32_bf16 v[28:31], v[138:141], v[174:177], v[28:31]
	v_mfma_f32_16x16x32_bf16 v[28:31], v[146:149], v[178:181], v[28:31]
	v_mfma_f32_16x16x32_bf16 v[12:15], v[138:141], v[204:207], v[12:15]
	v_mfma_f32_16x16x32_bf16 v[12:15], v[146:149], v[208:211], v[12:15]
	v_mfma_f32_16x16x32_bf16 v[8:11], v[150:153], v[204:207], v[8:11]
	v_mfma_f32_16x16x32_bf16 v[8:11], v[154:157], v[208:211], v[8:11]
	v_mfma_f32_16x16x32_bf16 v[24:27], v[150:153], v[174:177], v[24:27]
	v_mfma_f32_16x16x32_bf16 v[24:27], v[154:157], v[178:181], v[24:27]
	v_mfma_f32_16x16x32_bf16 v[40:43], v[150:153], v[166:169], v[40:43]
	v_mfma_f32_16x16x32_bf16 v[40:43], v[154:157], v[170:173], v[40:43]
	v_mfma_f32_16x16x32_bf16 v[56:59], v[150:153], v[158:161], v[56:59]
	v_mfma_f32_16x16x32_bf16 v[56:59], v[154:157], v[162:165], v[56:59]
	s_barrier
; #define PG8_STAGE(bufoff, gbase, voff) do { _Pragma("unroll") for (int _i = 0; _i < 2; ++_i) \
;         __builtin_amdgcn_global_load_lds((const unsigned*)((const char*)(gbase) + (voff)[_i]), (LAS unsigned*)(lds + (bufoff) + ldsw + _i * 8192), 16, 0, 0); } while (0)
; #define PG8_LDA(dst, b, h) do { _Pragma("unroll") for (int m = 0; m < 4; ++m) _Pragma("unroll") for (int k = 0; k < 2; ++k) dst[m][k] = *(const LAS bf16x8*)(lds + PG8_SA(b, h) + aoff + m * 2048 + k * 1024); } while (0)
; #define PG8_LDB(dst, b, h) do { _Pragma("unroll") for (int n = 0; n < 2; ++n) _Pragma("unroll") for (int k = 0; k < 2; ++k) dst[n][k] = *(const LAS bf16x8*)(lds + PG8_SB(b, h) + boff + n * 2048 + k * 1024); } while (0)
; #define PG8_MMA(ai, bj, At, Bt) do { __builtin_amdgcn_s_setprio(1); _Pragma("unroll") for (int m = 0; m < 4; ++m) _Pragma("unroll") for (int n = 0; n < 2; ++n) _Pragma("unroll") for (int k = 0; k < 2; ++k) \
;         acc[ai][bj][m][n] = __builtin_amdgcn_mfma_f32_16x16x32_bf16(Bt[n][k], At[m][k], acc[ai][bj][m][n], 0, 0, 0); __builtin_amdgcn_s_setprio(0); } while (0)
; #define PG8_WAIT_V(n) asm volatile("s_waitcnt vmcnt(" #n ")" ::: "memory")
; #define PG8_WAIT_L(n) asm volatile("s_waitcnt lgkmcnt(" #n ")" ::: "memory")
; #define PG8_BAR __builtin_amdgcn_s_barrier()
; #define PG8_SCHED __builtin_amdgcn_sched_barrier(0)
; template <class Epi>
; __device__ __forceinline__ void gemm_phase(LAS unsigned char* lds, const Gemm g, const StaticOrder& S, const Epi& E) {
;     ...
;             PG8_STAGE(PG8_SB(0, 1), b2 + hstep, voffB);
;             PG8_WAIT_V(6); PG8_BAR; PG8_MMA(1, 1, At, B1); PG8_BAR;
;             PG8_LDB(B0, 1, 0); PG8_SCHED; PG8_LDA(At, 1, 0); PG8_STAGE(PG8_SA(0, 1), a2 + hstep, voffA);
;             PG8_WAIT_L(8); PG8_BAR; PG8_WAIT_L(0); PG8_MMA(0, 0, At, B0); PG8_BAR; PG8_SCHED;
;             PG8_LDB(B1, 1, 1); PG8_STAGE(PG8_SB(1, 0), b3, voffB);
;             PG8_BAR; PG8_WAIT_L(0); PG8_MMA(0, 1, At, B1); PG8_BAR;
;             PG8_LDA(At, 1, 1); PG8_STAGE(PG8_SA(1, 0), a3, voffA);
	s_add_u32 s54, s30, 0x80000
	s_addc_u32 s55, s31, 0
	s_add_i32 s52, s56, s38
	s_mov_b32 m0, s52
	s_nop 0
	global_load_lds_dwordx4 v184, s[54:55]
	s_add_i32 m0, s52, 0x2000
	s_nop 0
	global_load_lds_dwordx4 v132, s[54:55]
	s_waitcnt vmcnt(6)
	s_barrier
	v_mfma_f32_16x16x32_bf16 v[52:55], v[212:215], v[158:161], v[52:55]
	v_mfma_f32_16x16x32_bf16 v[52:55], v[216:219], v[162:165], v[52:55]
	v_mfma_f32_16x16x32_bf16 v[36:39], v[212:215], v[166:169], v[36:39]
	v_mfma_f32_16x16x32_bf16 v[36:39], v[216:219], v[170:173], v[36:39]
	v_mfma_f32_16x16x32_bf16 v[20:23], v[212:215], v[174:177], v[20:23]
	v_mfma_f32_16x16x32_bf16 v[20:23], v[216:219], v[178:181], v[20:23]
	v_mfma_f32_16x16x32_bf16 v[4:7], v[212:215], v[204:207], v[4:7]
	v_mfma_f32_16x16x32_bf16 v[4:7], v[216:219], v[208:211], v[4:7]
	v_mfma_f32_16x16x32_bf16 v[0:3], v[220:223], v[204:207], v[0:3]
	v_mfma_f32_16x16x32_bf16 v[0:3], v[224:227], v[208:211], v[0:3]
	v_mfma_f32_16x16x32_bf16 v[16:19], v[220:223], v[174:177], v[16:19]
	v_mfma_f32_16x16x32_bf16 v[16:19], v[224:227], v[178:181], v[16:19]
	v_mfma_f32_16x16x32_bf16 v[32:35], v[220:223], v[166:169], v[32:35]
	v_mfma_f32_16x16x32_bf16 v[32:35], v[224:227], v[170:173], v[32:35]
	v_mfma_f32_16x16x32_bf16 v[48:51], v[220:223], v[158:161], v[48:51]
	v_mfma_f32_16x16x32_bf16 v[48:51], v[224:227], v[162:165], v[48:51]
	s_add_i32 s52, 0, 0x18000
	v_add_u32_e32 v154, s52, v143
	s_barrier
	ds_read_b128 v[138:141], v154
	ds_read_b128 v[146:149], v154 offset:1024
	ds_read_b128 v[150:153], v154 offset:2048
	ds_read_b128 v[154:157], v154 offset:3072
	s_add_u32 s34, s34, 0x80000
	s_addc_u32 s35, s35, 0
	s_mov_b32 m0, s39
	ds_read_b128 v[158:161], v145 offset:32768
	ds_read_b128 v[162:165], v145 offset:33792
	ds_read_b128 v[166:169], v145 offset:34816
	ds_read_b128 v[170:173], v145 offset:35840
	ds_read_b128 v[174:177], v145 offset:36864
	ds_read_b128 v[178:181], v145 offset:37888
	ds_read_b128 v[204:207], v145 offset:38912
	ds_read_b128 v[208:211], v145 offset:39936
	global_load_lds_dwordx4 v128, s[34:35]
	s_mov_b32 m0, s40
	s_nop 0
	global_load_lds_dwordx4 v130, s[34:35]
	s_waitcnt lgkmcnt(8)
	s_barrier
	s_waitcnt lgkmcnt(0)
	s_waitcnt lgkmcnt(0)
	v_mfma_f32_16x16x32_bf16 v[124:127], v[138:141], v[158:161], v[124:127]
	v_mfma_f32_16x16x32_bf16 v[124:127], v[146:149], v[162:165], v[124:127]
	v_mfma_f32_16x16x32_bf16 v[108:111], v[138:141], v[166:169], v[108:111]
	v_mfma_f32_16x16x32_bf16 v[108:111], v[146:149], v[170:173], v[108:111]
	v_mfma_f32_16x16x32_bf16 v[92:95], v[138:141], v[174:177], v[92:95]
	v_mfma_f32_16x16x32_bf16 v[92:95], v[146:149], v[178:181], v[92:95]
	v_mfma_f32_16x16x32_bf16 v[76:79], v[138:141], v[204:207], v[76:79]
	v_mfma_f32_16x16x32_bf16 v[76:79], v[146:149], v[208:211], v[76:79]
	v_mfma_f32_16x16x32_bf16 v[72:75], v[150:153], v[204:207], v[72:75]
	v_mfma_f32_16x16x32_bf16 v[72:75], v[154:157], v[208:211], v[72:75]
	v_mfma_f32_16x16x32_bf16 v[88:91], v[150:153], v[174:177], v[88:91]
	v_mfma_f32_16x16x32_bf16 v[88:91], v[154:157], v[178:181], v[88:91]
	v_mfma_f32_16x16x32_bf16 v[104:107], v[150:153], v[166:169], v[104:107]
	v_mfma_f32_16x16x32_bf16 v[104:107], v[154:157], v[170:173], v[104:107]
	v_mfma_f32_16x16x32_bf16 v[120:123], v[150:153], v[158:161], v[120:123]
	v_mfma_f32_16x16x32_bf16 v[120:123], v[154:157], v[162:165], v[120:123]
	s_barrier
	s_add_i32 s34, 0, 0x1c000
	s_add_i32 s35, s52, s38
	v_add_u32_e32 v187, s34, v143
	v_lshl_add_u64 v[182:183], v[182:183], 0, s[58:59]
	s_mov_b32 m0, s35
	ds_read_b128 v[212:215], v187
	ds_read_b128 v[216:219], v187 offset:1024
	ds_read_b128 v[220:223], v187 offset:2048
	ds_read_b128 v[224:227], v187 offset:3072
	global_load_lds_dwordx4 v[182:183], off
	v_lshl_add_u64 v[182:183], v[188:189], 0, s[58:59]
	s_add_i32 m0, s35, 0x2000
	s_nop 0
	global_load_lds_dwordx4 v[182:183], off
	s_barrier
	s_waitcnt lgkmcnt(0)
	s_waitcnt lgkmcnt(0)
	v_mfma_f32_16x16x32_bf16 v[116:119], v[212:215], v[158:161], v[116:119]
	v_mfma_f32_16x16x32_bf16 v[116:119], v[216:219], v[162:165], v[116:119]
	v_mfma_f32_16x16x32_bf16 v[100:103], v[212:215], v[166:169], v[100:103]
	v_mfma_f32_16x16x32_bf16 v[100:103], v[216:219], v[170:173], v[100:103]
	v_mfma_f32_16x16x32_bf16 v[84:87], v[212:215], v[174:177], v[84:87]
	v_mfma_f32_16x16x32_bf16 v[84:87], v[216:219], v[178:181], v[84:87]
	v_mfma_f32_16x16x32_bf16 v[68:71], v[212:215], v[204:207], v[68:71]
	v_mfma_f32_16x16x32_bf16 v[68:71], v[216:219], v[208:211], v[68:71]
	v_mfma_f32_16x16x32_bf16 v[64:67], v[220:223], v[204:207], v[64:67]
	v_mfma_f32_16x16x32_bf16 v[64:67], v[224:227], v[208:211], v[64:67]
	v_mfma_f32_16x16x32_bf16 v[80:83], v[220:223], v[174:177], v[80:83]
	v_mfma_f32_16x16x32_bf16 v[80:83], v[224:227], v[178:181], v[80:83]
	v_mfma_f32_16x16x32_bf16 v[96:99], v[220:223], v[166:169], v[96:99]
	v_mfma_f32_16x16x32_bf16 v[96:99], v[224:227], v[170:173], v[96:99]
	v_mfma_f32_16x16x32_bf16 v[112:115], v[220:223], v[158:161], v[112:115]
	v_mfma_f32_16x16x32_bf16 v[112:115], v[224:227], v[162:165], v[112:115]
	s_mov_b32 m0, s41
	v_lshl_add_u64 v[182:183], v[190:191], 0, s[58:59]
	s_barrier
; __device__ __forceinline__ float sigmoidf_(float x) { return __builtin_amdgcn_rcpf(1.0f + __builtin_amdgcn_exp2f(-1.4426950408889634f * x)); }
; #define PG8_STAGE(bufoff, gbase, voff) do { _Pragma("unroll") for (int _i = 0; _i < 2; ++_i) \
;         __builtin_amdgcn_global_load_lds((const unsigned*)((const char*)(gbase) + (voff)[_i]), (LAS unsigned*)(lds + (bufoff) + ldsw + _i * 8192), 16, 0, 0); } while (0)
; #define PG8_LDA(dst, b, h) do { _Pragma("unroll") for (int m = 0; m < 4; ++m) _Pragma("unroll") for (int k = 0; k < 2; ++k) dst[m][k] = *(const LAS bf16x8*)(lds + PG8_SA(b, h) + aoff + m * 2048 + k * 1024); } while (0)
; #define PG8_MMA(ai, bj, At, Bt) do { __builtin_amdgcn_s_setprio(1); _Pragma("unroll") for (int m = 0; m < 4; ++m) _Pragma("unroll") for (int n = 0; n < 2; ++n) _Pragma("unroll") for (int k = 0; k < 2; ++k) \
;         acc[ai][bj][m][n] = __builtin_amdgcn_mfma_f32_16x16x32_bf16(Bt[n][k], At[m][k], acc[ai][bj][m][n], 0, 0, 0); __builtin_amdgcn_s_setprio(0); } while (0)
; #define PG8_WAIT_V(n) asm volatile("s_waitcnt vmcnt(" #n ")" ::: "memory")
; #define PG8_WAIT_L(n) asm volatile("s_waitcnt lgkmcnt(" #n ")" ::: "memory")
; #define PG8_BAR __builtin_amdgcn_s_barrier()
; #define PG8_SCHED __builtin_amdgcn_sched_barrier(0)
; template <class Epi>
; __device__ __forceinline__ void gemm_phase(LAS unsigned char* lds, const Gemm g, const StaticOrder& S, const Epi& E) {
;     ...
;             PG8_LDA(At, 1, 1); PG8_STAGE(PG8_SA(1, 0), a3, voffA);
;             PG8_BAR; PG8_WAIT_L(0); PG8_MMA(1, 0, At, B0); PG8_BAR; PG8_SCHED;
;             PG8_STAGE(PG8_SB(1, 1), b3 + hstep, voffB);
;             PG8_WAIT_V(6); PG8_BAR; PG8_MMA(1, 1, At, B1); PG8_BAR;
;     __device__ __forceinline__ void operator()(const Acc& acc, const Unit& u, int wr, int wc, int fr, int fq) const {
;     ...
;                 for (int bj = 0; bj < 2; ++bj) { f32x4 v0 = acc[ai][bj][m][0], v1 = acc[ai][bj][m][1];
;                     if (act) {
; #pragma unroll
;                         for (int j = 0; j < 4; ++j) { v0[j] = sigmoidf_(v0[j]); v1[j] = sigmoidf_(v1[j]); } }
	ds_read_b128 v[158:161], v145 offset:49152
	ds_read_b128 v[162:165], v145 offset:50176
	ds_read_b128 v[166:169], v145 offset:51200
	ds_read_b128 v[170:173], v145 offset:52224
	ds_read_b128 v[174:177], v145 offset:53248
	ds_read_b128 v[178:181], v145 offset:54272
	ds_read_b128 v[204:207], v145 offset:55296
	ds_read_b128 v[208:211], v145 offset:56320
	global_load_lds_dwordx4 v[182:183], off
	v_lshl_add_u64 v[182:183], v[192:193], 0, s[58:59]
	s_mov_b32 m0, s42
	s_nop 0
	global_load_lds_dwordx4 v[182:183], off
	s_barrier
	s_waitcnt lgkmcnt(0)
	s_waitcnt lgkmcnt(0)
	v_mfma_f32_16x16x32_bf16 v[60:63], v[138:141], v[158:161], v[60:63]
	v_mfma_f32_16x16x32_bf16 v[60:63], v[146:149], v[162:165], v[60:63]
	v_mfma_f32_16x16x32_bf16 v[44:47], v[138:141], v[166:169], v[44:47]
	v_mfma_f32_16x16x32_bf16 v[44:47], v[146:149], v[170:173], v[44:47]
	v_mfma_f32_16x16x32_bf16 v[28:31], v[138:141], v[174:177], v[28:31]
	v_mfma_f32_16x16x32_bf16 v[28:31], v[146:149], v[178:181], v[28:31]
	v_mfma_f32_16x16x32_bf16 v[12:15], v[138:141], v[204:207], v[12:15]
	v_mfma_f32_16x16x32_bf16 v[12:15], v[146:149], v[208:211], v[12:15]
	v_mfma_f32_16x16x32_bf16 v[8:11], v[150:153], v[204:207], v[8:11]
	v_mfma_f32_16x16x32_bf16 v[8:11], v[154:157], v[208:211], v[8:11]
	v_mfma_f32_16x16x32_bf16 v[24:27], v[150:153], v[174:177], v[24:27]
	v_mfma_f32_16x16x32_bf16 v[24:27], v[154:157], v[178:181], v[24:27]
	v_mfma_f32_16x16x32_bf16 v[40:43], v[150:153], v[166:169], v[40:43]
	v_mfma_f32_16x16x32_bf16 v[40:43], v[154:157], v[170:173], v[40:43]
	v_mfma_f32_16x16x32_bf16 v[56:59], v[150:153], v[158:161], v[56:59]
	v_mfma_f32_16x16x32_bf16 v[56:59], v[154:157], v[162:165], v[56:59]
	s_barrier
	s_add_u32 s30, s30, 0x80080
	s_addc_u32 s31, s31, 0
	s_add_i32 s34, s34, s38
	s_mov_b32 m0, s34
	s_nop 0
	global_load_lds_dwordx4 v184, s[30:31]
	s_add_i32 m0, s34, 0x2000
	s_nop 0
	global_load_lds_dwordx4 v132, s[30:31]
	s_waitcnt vmcnt(6)
	s_barrier
	v_mfma_f32_16x16x32_bf16 v[52:55], v[212:215], v[158:161], v[52:55]
	v_mfma_f32_16x16x32_bf16 v[52:55], v[216:219], v[162:165], v[52:55]
	v_mfma_f32_16x16x32_bf16 v[36:39], v[212:215], v[166:169], v[36:39]
	v_mfma_f32_16x16x32_bf16 v[36:39], v[216:219], v[170:173], v[36:39]
	v_mfma_f32_16x16x32_bf16 v[20:23], v[212:215], v[174:177], v[20:23]
	v_mfma_f32_16x16x32_bf16 v[20:23], v[216:219], v[178:181], v[20:23]
	v_mfma_f32_16x16x32_bf16 v[4:7], v[212:215], v[204:207], v[4:7]
	v_mfma_f32_16x16x32_bf16 v[4:7], v[216:219], v[208:211], v[4:7]
	v_mfma_f32_16x16x32_bf16 v[0:3], v[220:223], v[204:207], v[0:3]
	v_mfma_f32_16x16x32_bf16 v[0:3], v[224:227], v[208:211], v[0:3]
	v_mfma_f32_16x16x32_bf16 v[16:19], v[220:223], v[174:177], v[16:19]
	v_mfma_f32_16x16x32_bf16 v[16:19], v[224:227], v[178:181], v[16:19]
	v_mfma_f32_16x16x32_bf16 v[32:35], v[220:223], v[166:169], v[32:35]
	v_mfma_f32_16x16x32_bf16 v[32:35], v[224:227], v[170:173], v[32:35]
	v_mfma_f32_16x16x32_bf16 v[48:51], v[220:223], v[158:161], v[48:51]
	v_mfma_f32_16x16x32_bf16 v[48:51], v[224:227], v[162:165], v[48:51]
	s_add_i32 s51, s51, 2
	s_add_u32 s8, s8, 0x100
	s_addc_u32 s9, s9, 0
	s_add_u32 s47, s47, 0x100
	s_addc_u32 s50, s50, 0
	s_cmp_gt_u32 s51, 29
	s_barrier
	s_cbranch_scc0 .LBB0_490
	v_cndmask_b32_e64 v138, 0, 1, s[16:17]
	v_cmp_ne_u32_e64 s[8:9], 1, v138
	s_andn2_b64 vcc, exec, s[16:17]
	s_cbranch_vccnz .LBB0_493
	v_mul_f32_e32 v124, 0xbfb8aa3b, v124
	v_mul_f32_e32 v120, 0xbfb8aa3b, v120
	v_mul_f32_e32 v125, 0xbfb8aa3b, v125
	v_mul_f32_e32 v121, 0xbfb8aa3b, v121
	v_mul_f32_e32 v126, 0xbfb8aa3b, v126
	v_mul_f32_e32 v122, 0xbfb8aa3b, v122
	v_mul_f32_e32 v127, 0xbfb8aa3b, v127
	v_mul_f32_e32 v123, 0xbfb8aa3b, v123
	v_exp_f32_e32 v124, v124
	v_exp_f32_e32 v120, v120
	v_exp_f32_e32 v125, v125
	v_exp_f32_e32 v121, v121
	v_exp_f32_e32 v126, v126
	v_exp_f32_e32 v122, v122
	v_exp_f32_e32 v127, v127
	v_exp_f32_e32 v123, v123
	v_add_f32_e32 v124, 1.0, v124
	v_add_f32_e32 v120, 1.0, v120
	v_add_f32_e32 v125, 1.0, v125
	v_add_f32_e32 v121, 1.0, v121
	v_add_f32_e32 v126, 1.0, v126
	v_add_f32_e32 v122, 1.0, v122
	v_add_f32_e32 v127, 1.0, v127
	v_add_f32_e32 v123, 1.0, v123
	v_rcp_f32_e32 v124, v124
	v_rcp_f32_e32 v120, v120
	v_rcp_f32_e32 v125, v125
	v_rcp_f32_e32 v121, v121
	v_rcp_f32_e32 v126, v126
	v_rcp_f32_e32 v122, v122
	v_rcp_f32_e32 v127, v127
	v_rcp_f32_e32 v123, v123

; #define PG8_STAGE(bufoff, gbase, voff) do { _Pragma("unroll") for (int _i = 0; _i < 2; ++_i) \
;         __builtin_amdgcn_global_load_lds((const unsigned*)((const char*)(gbase) + (voff)[_i]), (LAS unsigned*)(lds + (bufoff) + ldsw + _i * 8192), 16, 0, 0); } while (0)
; #define PG8_LDA(dst, b, h) do { _Pragma("unroll") for (int m = 0; m < 4; ++m) _Pragma("unroll") for (int k = 0; k < 2; ++k) dst[m][k] = *(const LAS bf16x8*)(lds + PG8_SA(b, h) + aoff + m * 2048 + k * 1024); } while (0)
; #define PG8_LDB(dst, b, h) do { _Pragma("unroll") for (int n = 0; n < 2; ++n) _Pragma("unroll") for (int k = 0; k < 2; ++k) dst[n][k] = *(const LAS bf16x8*)(lds + PG8_SB(b, h) + boff + n * 2048 + k * 1024); } while (0)
; #define PG8_MMA(ai, bj, At, Bt) do { __builtin_amdgcn_s_setprio(1); _Pragma("unroll") for (int m = 0; m < 4; ++m) _Pragma("unroll") for (int n = 0; n < 2; ++n) _Pragma("unroll") for (int k = 0; k < 2; ++k) \
;         acc[ai][bj][m][n] = __builtin_amdgcn_mfma_f32_16x16x32_bf16(Bt[n][k], At[m][k], acc[ai][bj][m][n], 0, 0, 0); __builtin_amdgcn_s_setprio(0); } while (0)
; #define PG8_WAIT_L(n) asm volatile("s_waitcnt lgkmcnt(" #n ")" ::: "memory")
; #define PG8_BAR __builtin_amdgcn_s_barrier()
; #define PG8_SCHED __builtin_amdgcn_sched_barrier(0)
; template <class Epi>
; __device__ __forceinline__ void gemm_phase(LAS unsigned char* lds, const Gemm g, const StaticOrder& S, const Epi& E) {
;     ...
;         for (int t = 0; t < nt; t += 2) {
;             const bool last = (t == nt - 2);
;             const char* a1 = cA + (size_t)(t + 1) * kstep;
;             const char* a2 = last ? nA : cA + (size_t)(t + 2) * kstep; const char* b2 = last ? nB : cB + (size_t)(t + 2) * kstep;
;             const char* a3 = a2 + kstep; const char* b3 = b2 + kstep;
;             PG8_LDB(B0, 0, 0); PG8_SCHED; PG8_LDA(At, 0, 0); PG8_STAGE(PG8_SA(1, 1), a1 + hstep, voffA);
;             PG8_WAIT_L(8); PG8_BAR; PG8_WAIT_L(0); PG8_MMA(0, 0, At, B0); PG8_BAR; PG8_SCHED;
;             PG8_LDB(B1, 0, 1); PG8_STAGE(PG8_SB(0, 0), b2, voffB);
;             PG8_BAR; PG8_WAIT_L(0); PG8_MMA(0, 1, At, B1); PG8_BAR;
;             PG8_LDA(At, 0, 1); PG8_STAGE(PG8_SA(0, 0), a2, voffA);
;             PG8_BAR; PG8_WAIT_L(0); PG8_MMA(1, 0, At, B0); PG8_BAR; PG8_SCHED;
.LBB0_721:
	s_add_u32 s18, s16, 0xfff80080
	s_addc_u32 s19, s17, -1
	s_add_i32 s39, 0, 0x10000
	v_add_u32_e32 v154, s39, v139
	ds_read_b128 v[142:145], v154
	ds_read_b128 v[146:149], v154 offset:1024
	ds_read_b128 v[150:153], v154 offset:2048
	ds_read_b128 v[154:157], v154 offset:3072
	s_cmp_eq_u32 s38, 28
	s_cselect_b32 s21, s9, s19
	s_cselect_b32 s20, s34, s18
	s_cselect_b32 s19, s1, s37
	s_cselect_b32 s18, s35, s36
	s_add_i32 m0, s15, 0xc000
	ds_read_b128 v[158:161], v141
	ds_read_b128 v[162:165], v141 offset:1024
	ds_read_b128 v[166:169], v141 offset:2048
	ds_read_b128 v[170:173], v141 offset:3072
	ds_read_b128 v[174:177], v141 offset:4096
	ds_read_b128 v[178:181], v141 offset:5120
	ds_read_b128 v[208:211], v141 offset:6144
	ds_read_b128 v[212:215], v141 offset:7168
	global_load_lds_dwordx4 v134, s[16:17]
	s_add_i32 m0, s15, 0xe000
	s_nop 0
	global_load_lds_dwordx4 v136, s[16:17]
	s_waitcnt lgkmcnt(8)
	s_barrier
	s_waitcnt lgkmcnt(0)
	s_waitcnt lgkmcnt(0)
	v_mfma_f32_16x16x32_bf16 v[124:127], v[142:145], v[158:161], v[124:127]
	v_mfma_f32_16x16x32_bf16 v[124:127], v[146:149], v[162:165], v[124:127]
	v_mfma_f32_16x16x32_bf16 v[108:111], v[142:145], v[166:169], v[108:111]
	v_mfma_f32_16x16x32_bf16 v[108:111], v[146:149], v[170:173], v[108:111]
	v_mfma_f32_16x16x32_bf16 v[92:95], v[142:145], v[174:177], v[92:95]
	v_mfma_f32_16x16x32_bf16 v[92:95], v[146:149], v[178:181], v[92:95]
	v_mfma_f32_16x16x32_bf16 v[76:79], v[142:145], v[208:211], v[76:79]
	v_mfma_f32_16x16x32_bf16 v[76:79], v[146:149], v[212:215], v[76:79]
	v_mfma_f32_16x16x32_bf16 v[68:71], v[150:153], v[208:211], v[68:71]
	v_mfma_f32_16x16x32_bf16 v[68:71], v[154:157], v[212:215], v[68:71]
	v_mfma_f32_16x16x32_bf16 v[84:87], v[150:153], v[174:177], v[84:87]
	v_mfma_f32_16x16x32_bf16 v[84:87], v[154:157], v[178:181], v[84:87]
	v_mfma_f32_16x16x32_bf16 v[100:103], v[150:153], v[166:169], v[100:103]
	v_mfma_f32_16x16x32_bf16 v[100:103], v[154:157], v[170:173], v[100:103]
	v_mfma_f32_16x16x32_bf16 v[116:119], v[150:153], v[158:161], v[116:119]
	v_mfma_f32_16x16x32_bf16 v[116:119], v[154:157], v[162:165], v[116:119]
	s_barrier
	s_add_i32 s42, 0, 0x14000
	v_add_u32_e32 v182, s42, v139
	s_add_i32 s39, s39, s24
	ds_read_b128 v[216:219], v182
	ds_read_b128 v[220:223], v182 offset:1024
	ds_read_b128 v[224:227], v182 offset:2048
	ds_read_b128 v[228:231], v182 offset:3072
	v_lshl_add_u64 v[182:183], s[18:19], 0, v[184:185]
	s_mov_b32 m0, s39
	v_lshl_add_u64 v[204:205], s[18:19], 0, v[128:129]
	global_load_lds_dwordx4 v[182:183], off
	s_add_i32 m0, s39, 0x2000
	s_nop 0
	global_load_lds_dwordx4 v[204:205], off
	s_barrier
	s_waitcnt lgkmcnt(0)
	s_waitcnt lgkmcnt(0)
	v_mfma_f32_16x16x32_bf16 v[120:123], v[216:219], v[158:161], v[120:123]
	v_mfma_f32_16x16x32_bf16 v[120:123], v[220:223], v[162:165], v[120:123]
	v_mfma_f32_16x16x32_bf16 v[104:107], v[216:219], v[166:169], v[104:107]
	v_mfma_f32_16x16x32_bf16 v[104:107], v[220:223], v[170:173], v[104:107]
	v_mfma_f32_16x16x32_bf16 v[88:91], v[216:219], v[174:177], v[88:91]
	v_mfma_f32_16x16x32_bf16 v[88:91], v[220:223], v[178:181], v[88:91]
	v_mfma_f32_16x16x32_bf16 v[72:75], v[216:219], v[208:211], v[72:75]
	v_mfma_f32_16x16x32_bf16 v[72:75], v[220:223], v[212:215], v[72:75]
	v_mfma_f32_16x16x32_bf16 v[64:67], v[224:227], v[208:211], v[64:67]
	v_mfma_f32_16x16x32_bf16 v[64:67], v[228:231], v[212:215], v[64:67]
	v_mfma_f32_16x16x32_bf16 v[80:83], v[224:227], v[174:177], v[80:83]
	v_mfma_f32_16x16x32_bf16 v[80:83], v[228:231], v[178:181], v[80:83]
	v_mfma_f32_16x16x32_bf16 v[96:99], v[224:227], v[166:169], v[96:99]
	v_mfma_f32_16x16x32_bf16 v[96:99], v[228:231], v[170:173], v[96:99]
	v_mfma_f32_16x16x32_bf16 v[112:115], v[224:227], v[158:161], v[112:115]
	v_mfma_f32_16x16x32_bf16 v[112:115], v[228:231], v[162:165], v[112:115]
	s_mov_b32 m0, s15
	v_lshl_add_u64 v[206:207], s[20:21], 0, v[132:133]
	s_barrier
	ds_read_b128 v[158:161], v141 offset:16384
	ds_read_b128 v[162:165], v141 offset:17408
	ds_read_b128 v[166:169], v141 offset:18432
	ds_read_b128 v[170:173], v141 offset:19456
	ds_read_b128 v[174:177], v141 offset:20480
	ds_read_b128 v[178:181], v141 offset:21504
	ds_read_b128 v[208:211], v141 offset:22528
	ds_read_b128 v[212:215], v141 offset:23552
	global_load_lds_dwordx4 v[206:207], off
	v_lshl_add_u64 v[232:233], s[20:21], 0, v[130:131]
	s_mov_b32 m0, s26
	s_nop 0
	global_load_lds_dwordx4 v[232:233], off
	s_barrier
	s_waitcnt lgkmcnt(0)
	s_waitcnt lgkmcnt(0)
	v_mfma_f32_16x16x32_bf16 v[60:63], v[142:145], v[158:161], v[60:63]
	v_mfma_f32_16x16x32_bf16 v[60:63], v[146:149], v[162:165], v[60:63]
	v_mfma_f32_16x16x32_bf16 v[44:47], v[142:145], v[166:169], v[44:47]
	v_mfma_f32_16x16x32_bf16 v[44:47], v[146:149], v[170:173], v[44:47]
	v_mfma_f32_16x16x32_bf16 v[28:31], v[142:145], v[174:177], v[28:31]
	v_mfma_f32_16x16x32_bf16 v[28:31], v[146:149], v[178:181], v[28:31]
	v_mfma_f32_16x16x32_bf16 v[12:15], v[142:145], v[208:211], v[12:15]
	v_mfma_f32_16x16x32_bf16 v[12:15], v[146:149], v[212:215], v[12:15]
	v_mfma_f32_16x16x32_bf16 v[4:7], v[150:153], v[208:211], v[4:7]
	v_mfma_f32_16x16x32_bf16 v[4:7], v[154:157], v[212:215], v[4:7]
	v_mfma_f32_16x16x32_bf16 v[20:23], v[150:153], v[174:177], v[20:23]
	v_mfma_f32_16x16x32_bf16 v[20:23], v[154:157], v[178:181], v[20:23]
	v_mfma_f32_16x16x32_bf16 v[36:39], v[150:153], v[166:169], v[36:39]
	v_mfma_f32_16x16x32_bf16 v[36:39], v[154:157], v[170:173], v[36:39]
	v_mfma_f32_16x16x32_bf16 v[52:55], v[150:153], v[158:161], v[52:55]
	v_mfma_f32_16x16x32_bf16 v[52:55], v[154:157], v[162:165], v[52:55]
	s_barrier
; #define PG8_STAGE(bufoff, gbase, voff) do { _Pragma("unroll") for (int _i = 0; _i < 2; ++_i) \
;         __builtin_amdgcn_global_load_lds((const unsigned*)((const char*)(gbase) + (voff)[_i]), (LAS unsigned*)(lds + (bufoff) + ldsw + _i * 8192), 16, 0, 0); } while (0)
; #define PG8_LDA(dst, b, h) do { _Pragma("unroll") for (int m = 0; m < 4; ++m) _Pragma("unroll") for (int k = 0; k < 2; ++k) dst[m][k] = *(const LAS bf16x8*)(lds + PG8_SA(b, h) + aoff + m * 2048 + k * 1024); } while (0)
; #define PG8_LDB(dst, b, h) do { _Pragma("unroll") for (int n = 0; n < 2; ++n) _Pragma("unroll") for (int k = 0; k < 2; ++k) dst[n][k] = *(const LAS bf16x8*)(lds + PG8_SB(b, h) + boff + n * 2048 + k * 1024); } while (0)
; #define PG8_MMA(ai, bj, At, Bt) do { __builtin_amdgcn_s_setprio(1); _Pragma("unroll") for (int m = 0; m < 4; ++m) _Pragma("unroll") for (int n = 0; n < 2; ++n) _Pragma("unroll") for (int k = 0; k < 2; ++k) \
;         acc[ai][bj][m][n] = __builtin_amdgcn_mfma_f32_16x16x32_bf16(Bt[n][k], At[m][k], acc[ai][bj][m][n], 0, 0, 0); __builtin_amdgcn_s_setprio(0); } while (0)
; #define PG8_WAIT_V(n) asm volatile("s_waitcnt vmcnt(" #n ")" ::: "memory")
; #define PG8_WAIT_L(n) asm volatile("s_waitcnt lgkmcnt(" #n ")" ::: "memory")
; #define PG8_BAR __builtin_amdgcn_s_barrier()
; #define PG8_SCHED __builtin_amdgcn_sched_barrier(0)
; template <class Epi>
; __device__ __forceinline__ void gemm_phase(LAS unsigned char* lds, const Gemm g, const StaticOrder& S, const Epi& E) {
;     ...
;             PG8_STAGE(PG8_SB(0, 1), b2 + hstep, voffB);
;             PG8_WAIT_V(6); PG8_BAR; PG8_MMA(1, 1, At, B1); PG8_BAR;
;             PG8_LDB(B0, 1, 0); PG8_SCHED; PG8_LDA(At, 1, 0); PG8_STAGE(PG8_SA(0, 1), a2 + hstep, voffA);
;             PG8_WAIT_L(8); PG8_BAR; PG8_WAIT_L(0); PG8_MMA(0, 0, At, B0); PG8_BAR; PG8_SCHED;
;             PG8_LDB(B1, 1, 1); PG8_STAGE(PG8_SB(1, 0), b3, voffB);
;             PG8_BAR; PG8_WAIT_L(0); PG8_MMA(0, 1, At, B1); PG8_BAR;
;             PG8_LDA(At, 1, 1); PG8_STAGE(PG8_SA(1, 0), a3, voffA);
	s_add_u32 s40, s18, 0x80000
	s_addc_u32 s41, s19, 0
	s_add_i32 s39, s42, s24
	s_mov_b32 m0, s39
	s_nop 0
	global_load_lds_dwordx4 v184, s[40:41]
	s_add_i32 m0, s39, 0x2000
	s_nop 0
	global_load_lds_dwordx4 v128, s[40:41]
	s_waitcnt vmcnt(6)
	s_barrier
	v_mfma_f32_16x16x32_bf16 v[56:59], v[216:219], v[158:161], v[56:59]
	v_mfma_f32_16x16x32_bf16 v[56:59], v[220:223], v[162:165], v[56:59]
	v_mfma_f32_16x16x32_bf16 v[40:43], v[216:219], v[166:169], v[40:43]
	v_mfma_f32_16x16x32_bf16 v[40:43], v[220:223], v[170:173], v[40:43]
	v_mfma_f32_16x16x32_bf16 v[24:27], v[216:219], v[174:177], v[24:27]
	v_mfma_f32_16x16x32_bf16 v[24:27], v[220:223], v[178:181], v[24:27]
	v_mfma_f32_16x16x32_bf16 v[8:11], v[216:219], v[208:211], v[8:11]
	v_mfma_f32_16x16x32_bf16 v[8:11], v[220:223], v[212:215], v[8:11]
	v_mfma_f32_16x16x32_bf16 v[0:3], v[224:227], v[208:211], v[0:3]
	v_mfma_f32_16x16x32_bf16 v[0:3], v[228:231], v[212:215], v[0:3]
	v_mfma_f32_16x16x32_bf16 v[16:19], v[224:227], v[174:177], v[16:19]
	v_mfma_f32_16x16x32_bf16 v[16:19], v[228:231], v[178:181], v[16:19]
	v_mfma_f32_16x16x32_bf16 v[32:35], v[224:227], v[166:169], v[32:35]
	v_mfma_f32_16x16x32_bf16 v[32:35], v[228:231], v[170:173], v[32:35]
	v_mfma_f32_16x16x32_bf16 v[48:51], v[224:227], v[158:161], v[48:51]
	v_mfma_f32_16x16x32_bf16 v[48:51], v[228:231], v[162:165], v[48:51]
	s_add_i32 s39, 0, 0x18000
	v_add_u32_e32 v154, s39, v139
	s_barrier
	ds_read_b128 v[142:145], v154
	ds_read_b128 v[146:149], v154 offset:1024
	ds_read_b128 v[150:153], v154 offset:2048
	ds_read_b128 v[154:157], v154 offset:3072
	s_add_u32 s20, s20, 0x80000
	s_addc_u32 s21, s21, 0
	s_mov_b32 m0, s27
	ds_read_b128 v[158:161], v141 offset:32768
	ds_read_b128 v[162:165], v141 offset:33792
	ds_read_b128 v[166:169], v141 offset:34816
	ds_read_b128 v[170:173], v141 offset:35840
	ds_read_b128 v[174:177], v141 offset:36864
	ds_read_b128 v[178:181], v141 offset:37888
	ds_read_b128 v[208:211], v141 offset:38912
	ds_read_b128 v[212:215], v141 offset:39936
	global_load_lds_dwordx4 v132, s[20:21]
	s_mov_b32 m0, s28
	s_nop 0
	global_load_lds_dwordx4 v130, s[20:21]
	s_waitcnt lgkmcnt(8)
	s_barrier
	s_waitcnt lgkmcnt(0)
	s_waitcnt lgkmcnt(0)
	v_mfma_f32_16x16x32_bf16 v[124:127], v[142:145], v[158:161], v[124:127]
	v_mfma_f32_16x16x32_bf16 v[124:127], v[146:149], v[162:165], v[124:127]
	v_mfma_f32_16x16x32_bf16 v[108:111], v[142:145], v[166:169], v[108:111]
	v_mfma_f32_16x16x32_bf16 v[108:111], v[146:149], v[170:173], v[108:111]
	v_mfma_f32_16x16x32_bf16 v[92:95], v[142:145], v[174:177], v[92:95]
	v_mfma_f32_16x16x32_bf16 v[92:95], v[146:149], v[178:181], v[92:95]
	v_mfma_f32_16x16x32_bf16 v[76:79], v[142:145], v[208:211], v[76:79]
	v_mfma_f32_16x16x32_bf16 v[76:79], v[146:149], v[212:215], v[76:79]
	v_mfma_f32_16x16x32_bf16 v[68:71], v[150:153], v[208:211], v[68:71]
	v_mfma_f32_16x16x32_bf16 v[68:71], v[154:157], v[212:215], v[68:71]
	v_mfma_f32_16x16x32_bf16 v[84:87], v[150:153], v[174:177], v[84:87]
	v_mfma_f32_16x16x32_bf16 v[84:87], v[154:157], v[178:181], v[84:87]
	v_mfma_f32_16x16x32_bf16 v[100:103], v[150:153], v[166:169], v[100:103]
	v_mfma_f32_16x16x32_bf16 v[100:103], v[154:157], v[170:173], v[100:103]
	v_mfma_f32_16x16x32_bf16 v[116:119], v[150:153], v[158:161], v[116:119]
	v_mfma_f32_16x16x32_bf16 v[116:119], v[154:157], v[162:165], v[116:119]
	s_barrier
	s_add_i32 s20, 0, 0x1c000
	s_add_i32 s21, s39, s24
	v_add_u32_e32 v187, s20, v139
	v_lshl_add_u64 v[182:183], v[182:183], 0, s[58:59]
	s_mov_b32 m0, s21
	ds_read_b128 v[216:219], v187
	ds_read_b128 v[220:223], v187 offset:1024
	ds_read_b128 v[224:227], v187 offset:2048
	ds_read_b128 v[228:231], v187 offset:3072
	global_load_lds_dwordx4 v[182:183], off
	v_lshl_add_u64 v[182:183], v[204:205], 0, s[58:59]
	s_add_i32 m0, s21, 0x2000
	s_nop 0
	global_load_lds_dwordx4 v[182:183], off
	s_barrier
	s_waitcnt lgkmcnt(0)
	s_waitcnt lgkmcnt(0)
	v_mfma_f32_16x16x32_bf16 v[120:123], v[216:219], v[158:161], v[120:123]
	v_mfma_f32_16x16x32_bf16 v[120:123], v[220:223], v[162:165], v[120:123]
	v_mfma_f32_16x16x32_bf16 v[104:107], v[216:219], v[166:169], v[104:107]
	v_mfma_f32_16x16x32_bf16 v[104:107], v[220:223], v[170:173], v[104:107]
	v_mfma_f32_16x16x32_bf16 v[88:91], v[216:219], v[174:177], v[88:91]
	v_mfma_f32_16x16x32_bf16 v[88:91], v[220:223], v[178:181], v[88:91]
	v_mfma_f32_16x16x32_bf16 v[72:75], v[216:219], v[208:211], v[72:75]
	v_mfma_f32_16x16x32_bf16 v[72:75], v[220:223], v[212:215], v[72:75]
	v_mfma_f32_16x16x32_bf16 v[64:67], v[224:227], v[208:211], v[64:67]
	v_mfma_f32_16x16x32_bf16 v[64:67], v[228:231], v[212:215], v[64:67]
	v_mfma_f32_16x16x32_bf16 v[80:83], v[224:227], v[174:177], v[80:83]
	v_mfma_f32_16x16x32_bf16 v[80:83], v[228:231], v[178:181], v[80:83]
	v_mfma_f32_16x16x32_bf16 v[96:99], v[224:227], v[166:169], v[96:99]
	v_mfma_f32_16x16x32_bf16 v[96:99], v[228:231], v[170:173], v[96:99]
	v_mfma_f32_16x16x32_bf16 v[112:115], v[224:227], v[158:161], v[112:115]
	v_mfma_f32_16x16x32_bf16 v[112:115], v[228:231], v[162:165], v[112:115]
	s_mov_b32 m0, s29
	v_lshl_add_u64 v[182:183], v[206:207], 0, s[58:59]
	s_barrier
	ds_read_b128 v[158:161], v141 offset:49152
	ds_read_b128 v[162:165], v141 offset:50176
	ds_read_b128 v[166:169], v141 offset:51200
	ds_read_b128 v[170:173], v141 offset:52224
	ds_read_b128 v[174:177], v141 offset:53248
	ds_read_b128 v[178:181], v141 offset:54272
	ds_read_b128 v[208:211], v141 offset:55296
	ds_read_b128 v[212:215], v141 offset:56320
	global_load_lds_dwordx4 v[182:183], off
	v_lshl_add_u64 v[182:183], v[232:233], 0, s[58:59]
	s_mov_b32 m0, s30
	s_nop 0
	global_load_lds_dwordx4 v[182:183], off
	s_barrier
; __device__ __forceinline__ unsigned pk2(float lo, float hi) { unsigned r; asm("v_cvt_pk_bf16_f32 %0, %1, %2" : "=v"(r) : "v"(lo), "v"(hi)); return r; }
; __device__ __forceinline__ float sigmoidf_(float x) { return __builtin_amdgcn_rcpf(1.0f + __builtin_amdgcn_exp2f(-1.4426950408889634f * x)); }
; #define PG8_STAGE(bufoff, gbase, voff) do { _Pragma("unroll") for (int _i = 0; _i < 2; ++_i) \
;         __builtin_amdgcn_global_load_lds((const unsigned*)((const char*)(gbase) + (voff)[_i]), (LAS unsigned*)(lds + (bufoff) + ldsw + _i * 8192), 16, 0, 0); } while (0)
; #define PG8_MMA(ai, bj, At, Bt) do { __builtin_amdgcn_s_setprio(1); _Pragma("unroll") for (int m = 0; m < 4; ++m) _Pragma("unroll") for (int n = 0; n < 2; ++n) _Pragma("unroll") for (int k = 0; k < 2; ++k) \
;         acc[ai][bj][m][n] = __builtin_amdgcn_mfma_f32_16x16x32_bf16(Bt[n][k], At[m][k], acc[ai][bj][m][n], 0, 0, 0); __builtin_amdgcn_s_setprio(0); } while (0)
; #define PG8_WAIT_V(n) asm volatile("s_waitcnt vmcnt(" #n ")" ::: "memory")
; #define PG8_WAIT_L(n) asm volatile("s_waitcnt lgkmcnt(" #n ")" ::: "memory")
; #define PG8_BAR __builtin_amdgcn_s_barrier()
; #define PG8_SCHED __builtin_amdgcn_sched_barrier(0)
; template <class Epi>
; __device__ __forceinline__ void gemm_phase(LAS unsigned char* lds, const Gemm g, const StaticOrder& S, const Epi& E) {
;     ...
;             PG8_BAR; PG8_WAIT_L(0); PG8_MMA(1, 0, At, B0); PG8_BAR; PG8_SCHED;
;             PG8_STAGE(PG8_SB(1, 1), b3 + hstep, voffB);
;             PG8_WAIT_V(6); PG8_BAR; PG8_MMA(1, 1, At, B1); PG8_BAR;
;     __device__ __forceinline__ void operator()(const Acc& acc, const Unit& u, int wr, int wc, int fr, int fq) const {
;         const int row0 = u.pm * 256 + wr * 64 + fr, col0 = u.pn * 128 + wc * 32 + 8 * fq;
; #pragma unroll
;         for (int ai = 0; ai < 2; ++ai)
; #pragma unroll
;             for (int m = 0; m < 4; ++m) {
;                 float h[8];
; #pragma unroll
;                 for (int n = 0; n < 2; ++n)
; #pragma unroll
;                     for (int j = 0; j < 4; ++j) { const float gv = acc[ai][0][m][n][j], uv = acc[ai][1][m][n][j]; h[n * 4 + j] = gv * sigmoidf_(gv) * uv; }
;                 u32x4 w; w.x = pk2(h[0], h[1]); w.y = pk2(h[2], h[3]); w.z = pk2(h[4], h[5]); w.w = pk2(h[6], h[7]);
;                 *(u32x4*)(H + (size_t)(row0 + ai * 128 + m * 16) * DFF + col0) = w;
	s_waitcnt lgkmcnt(0)
	s_waitcnt lgkmcnt(0)
	v_mfma_f32_16x16x32_bf16 v[60:63], v[142:145], v[158:161], v[60:63]
	v_mfma_f32_16x16x32_bf16 v[60:63], v[146:149], v[162:165], v[60:63]
	v_mfma_f32_16x16x32_bf16 v[44:47], v[142:145], v[166:169], v[44:47]
	v_mfma_f32_16x16x32_bf16 v[44:47], v[146:149], v[170:173], v[44:47]
	v_mfma_f32_16x16x32_bf16 v[28:31], v[142:145], v[174:177], v[28:31]
	v_mfma_f32_16x16x32_bf16 v[28:31], v[146:149], v[178:181], v[28:31]
	v_mfma_f32_16x16x32_bf16 v[12:15], v[142:145], v[208:211], v[12:15]
	v_mfma_f32_16x16x32_bf16 v[12:15], v[146:149], v[212:215], v[12:15]
	v_mfma_f32_16x16x32_bf16 v[4:7], v[150:153], v[208:211], v[4:7]
	v_mfma_f32_16x16x32_bf16 v[4:7], v[154:157], v[212:215], v[4:7]
	v_mfma_f32_16x16x32_bf16 v[20:23], v[150:153], v[174:177], v[20:23]
	v_mfma_f32_16x16x32_bf16 v[20:23], v[154:157], v[178:181], v[20:23]
	v_mfma_f32_16x16x32_bf16 v[36:39], v[150:153], v[166:169], v[36:39]
	v_mfma_f32_16x16x32_bf16 v[36:39], v[154:157], v[170:173], v[36:39]
	v_mfma_f32_16x16x32_bf16 v[52:55], v[150:153], v[158:161], v[52:55]
	v_mfma_f32_16x16x32_bf16 v[52:55], v[154:157], v[162:165], v[52:55]
	s_barrier
	s_add_u32 s18, s18, 0x80080
	s_addc_u32 s19, s19, 0
	s_add_i32 s20, s20, s24
	s_mov_b32 m0, s20
	s_nop 0
	global_load_lds_dwordx4 v184, s[18:19]
	s_add_i32 m0, s20, 0x2000
	s_nop 0
	global_load_lds_dwordx4 v128, s[18:19]
	s_waitcnt vmcnt(6)
	s_barrier
	v_mfma_f32_16x16x32_bf16 v[56:59], v[216:219], v[158:161], v[56:59]
	v_mfma_f32_16x16x32_bf16 v[56:59], v[220:223], v[162:165], v[56:59]
	v_mfma_f32_16x16x32_bf16 v[40:43], v[216:219], v[166:169], v[40:43]
	v_mfma_f32_16x16x32_bf16 v[40:43], v[220:223], v[170:173], v[40:43]
	v_mfma_f32_16x16x32_bf16 v[24:27], v[216:219], v[174:177], v[24:27]
	v_mfma_f32_16x16x32_bf16 v[24:27], v[220:223], v[178:181], v[24:27]
	v_mfma_f32_16x16x32_bf16 v[8:11], v[216:219], v[208:211], v[8:11]
	v_mfma_f32_16x16x32_bf16 v[8:11], v[220:223], v[212:215], v[8:11]
	v_mfma_f32_16x16x32_bf16 v[0:3], v[224:227], v[208:211], v[0:3]
	v_mfma_f32_16x16x32_bf16 v[0:3], v[228:231], v[212:215], v[0:3]
	v_mfma_f32_16x16x32_bf16 v[16:19], v[224:227], v[174:177], v[16:19]
	v_mfma_f32_16x16x32_bf16 v[16:19], v[228:231], v[178:181], v[16:19]
	v_mfma_f32_16x16x32_bf16 v[32:35], v[224:227], v[166:169], v[32:35]
	v_mfma_f32_16x16x32_bf16 v[32:35], v[228:231], v[170:173], v[32:35]
	v_mfma_f32_16x16x32_bf16 v[48:51], v[224:227], v[158:161], v[48:51]
	v_mfma_f32_16x16x32_bf16 v[48:51], v[228:231], v[162:165], v[48:51]
	s_add_i32 s38, s38, 2
	s_add_u32 s16, s16, 0x100
	s_addc_u32 s17, s17, 0
	s_add_u32 s36, s36, 0x100
	s_addc_u32 s37, s37, 0
	s_cmp_gt_u32 s38, 29
	s_barrier
	s_cbranch_scc0 .LBB0_721
	v_mul_f32_e32 v143, 0xbfb8aa3b, v124
	v_exp_f32_e32 v143, v143
	v_lshl_or_b32 v144, s3, 7, v140
	v_lshl_add_u32 v142, s14, 8, v138
	v_ashrrev_i32_e32 v145, 31, v144
	v_add_f32_e32 v143, 1.0, v143
	v_rcp_f32_e32 v143, v143
	s_movk_i32 s1, 0x2c00
	s_and_b64 vcc, exec, s[6:7]
	s_mov_b32 s3, s0
	v_mul_f32_e32 v124, v124, v143
	v_mul_f32_e32 v120, v124, v120
	v_mul_f32_e32 v124, 0xbfb8aa3b, v125
	v_exp_f32_e32 v124, v124
	s_mov_b32 s14, s8
	s_mov_b64 s[18:19], s[12:13]
	v_add_f32_e32 v124, 1.0, v124
	v_rcp_f32_e32 v124, v124
	s_nop 0
	v_mul_f32_e32 v124, v125, v124
	v_mul_f32_e32 v121, v124, v121
	v_mul_f32_e32 v124, 0xbfb8aa3b, v126
	v_exp_f32_e32 v124, v124
	s_nop 0
	v_add_f32_e32 v124, 1.0, v124
	v_rcp_f32_e32 v124, v124
	s_nop 0
	v_mul_f32_e32 v124, v126, v124
	v_mul_f32_e32 v122, v124, v122
	v_mul_f32_e32 v124, 0xbfb8aa3b, v127
	v_exp_f32_e32 v124, v124
	s_nop 0
	v_add_f32_e32 v124, 1.0, v124
	v_rcp_f32_e32 v124, v124
	s_nop 0
	v_mul_f32_e32 v124, v127, v124
	v_mul_f32_e32 v123, v124, v123
	v_mul_f32_e32 v124, 0xbfb8aa3b, v116
	v_exp_f32_e32 v124, v124
	s_nop 0
	v_add_f32_e32 v124, 1.0, v124
	v_rcp_f32_e32 v124, v124
	s_nop 0
	v_mul_f32_e32 v116, v116, v124
	v_mul_f32_e32 v112, v116, v112
	v_mul_f32_e32 v116, 0xbfb8aa3b, v117
	v_exp_f32_e32 v116, v116
	s_nop 0
	v_add_f32_e32 v116, 1.0, v116
	v_rcp_f32_e32 v116, v116
	s_nop 0
	v_mul_f32_e32 v116, v117, v116
	v_mul_f32_e32 v113, v116, v113
	v_mul_f32_e32 v116, 0xbfb8aa3b, v118
	v_exp_f32_e32 v116, v116
	v_cvt_pk_bf16_f32 v117, v122, v123
	s_nop 0
	v_add_f32_e32 v116, 1.0, v116
	v_rcp_f32_e32 v116, v116
	s_nop 0
	v_mul_f32_e32 v116, v118, v116
	v_mul_f32_e32 v114, v116, v114
	v_mul_f32_e32 v116, 0xbfb8aa3b, v119
	v_exp_f32_e32 v116, v116
	v_cvt_pk_bf16_f32 v118, v112, v113
	v_mov_b64_e32 v[112:113], s[66:67]
	v_add_f32_e32 v116, 1.0, v116
	v_rcp_f32_e32 v116, v116
	s_nop 0
	v_mul_f32_e32 v116, v119, v116
	v_mul_f32_e32 v115, v116, v115
	v_cvt_pk_bf16_f32 v116, v120, v121
	v_cvt_pk_bf16_f32 v119, v114, v115
	v_mad_i64_i32 v[120:121], s[16:17], v142, s1, v[112:113]
	v_lshlrev_b64 v[114:115], 1, v[144:145]
	v_lshl_add_u64 v[120:121], v[120:121], 0, v[114:115]
	global_store_dwordx4 v[120:121], v[116:119], off
	s_nop 1
	v_mul_f32_e32 v116, 0xbfb8aa3b, v108
	v_exp_f32_e32 v116, v116
	s_nop 0
	v_add_f32_e32 v116, 1.0, v116
	v_rcp_f32_e32 v116, v116
	s_nop 0
	v_mul_f32_e32 v108, v108, v116
	v_mul_f32_e32 v104, v108, v104
	v_mul_f32_e32 v108, 0xbfb8aa3b, v109
	v_exp_f32_e32 v108, v108
	s_nop 0
	v_add_f32_e32 v108, 1.0, v108
	v_rcp_f32_e32 v108, v108
	s_nop 0
	v_mul_f32_e32 v108, v109, v108
	v_mul_f32_e32 v105, v108, v105
	v_mul_f32_e32 v108, 0xbfb8aa3b, v110
	v_exp_f32_e32 v108, v108
	s_nop 0
	v_add_f32_e32 v108, 1.0, v108
	v_rcp_f32_e32 v108, v108
	s_nop 0
	v_mul_f32_e32 v108, v110, v108
	v_mul_f32_e32 v106, v108, v106
	v_mul_f32_e32 v108, 0xbfb8aa3b, v111
	v_exp_f32_e32 v108, v108
	s_nop 0
	v_add_f32_e32 v108, 1.0, v108
	v_rcp_f32_e32 v108, v108
	s_nop 0
; __device__ __forceinline__ unsigned pk2(float lo, float hi) { unsigned r; asm("v_cvt_pk_bf16_f32 %0, %1, %2" : "=v"(r) : "v"(lo), "v"(hi)); return r; }
; __device__ __forceinline__ float sigmoidf_(float x) { return __builtin_amdgcn_rcpf(1.0f + __builtin_amdgcn_exp2f(-1.4426950408889634f * x)); }
;     __device__ __forceinline__ void operator()(const Acc& acc, const Unit& u, int wr, int wc, int fr, int fq) const {
;     ...
;             for (int m = 0; m < 4; ++m) {
;                 float h[8];
; #pragma unroll
;                 for (int n = 0; n < 2; ++n)
; #pragma unroll
;                     for (int j = 0; j < 4; ++j) { const float gv = acc[ai][0][m][n][j], uv = acc[ai][1][m][n][j]; h[n * 4 + j] = gv * sigmoidf_(gv) * uv; }
;                 u32x4 w; w.x = pk2(h[0], h[1]); w.y = pk2(h[2], h[3]); w.z = pk2(h[4], h[5]); w.w = pk2(h[6], h[7]);
;                 *(u32x4*)(H + (size_t)(row0 + ai * 128 + m * 16) * DFF + col0) = w;
	v_mul_f32_e32 v108, v111, v108
	v_mul_f32_e32 v107, v108, v107
	v_mul_f32_e32 v108, 0xbfb8aa3b, v100
	v_exp_f32_e32 v108, v108
	s_nop 0
	v_add_f32_e32 v108, 1.0, v108
	v_rcp_f32_e32 v108, v108
	s_nop 0
	v_mul_f32_e32 v100, v100, v108
	v_mul_f32_e32 v100, v100, v96
	v_mul_f32_e32 v96, 0xbfb8aa3b, v101
	v_exp_f32_e32 v96, v96
	s_nop 0
	v_add_f32_e32 v96, 1.0, v96
	v_rcp_f32_e32 v96, v96
	s_nop 0
	v_mul_f32_e32 v96, v101, v96
	v_mul_f32_e32 v101, v96, v97
	v_mul_f32_e32 v96, 0xbfb8aa3b, v102
	v_exp_f32_e32 v96, v96
	v_cvt_pk_bf16_f32 v97, v106, v107
	s_nop 0
	v_add_f32_e32 v96, 1.0, v96
	v_rcp_f32_e32 v96, v96
	s_nop 0
	v_mul_f32_e32 v96, v102, v96
	v_mul_f32_e32 v102, v96, v98
	v_mul_f32_e32 v96, 0xbfb8aa3b, v103
	v_exp_f32_e32 v96, v96
	v_cvt_pk_bf16_f32 v98, v100, v101
	v_or_b32_e32 v100, 16, v142
	v_mad_i64_i32 v[100:101], s[16:17], v100, s1, v[112:113]
	v_add_f32_e32 v96, 1.0, v96
	v_rcp_f32_e32 v96, v96
	v_lshl_add_u64 v[100:101], v[100:101], 0, v[114:115]
	v_mul_f32_e32 v96, v103, v96
	v_mul_f32_e32 v99, v96, v99
	v_cvt_pk_bf16_f32 v96, v104, v105
	v_cvt_pk_bf16_f32 v99, v102, v99
	global_store_dwordx4 v[100:101], v[96:99], off
	s_nop 1
	v_mul_f32_e32 v96, 0xbfb8aa3b, v92
	v_exp_f32_e32 v96, v96
	s_nop 0
	v_add_f32_e32 v96, 1.0, v96
	v_rcp_f32_e32 v96, v96
	s_nop 0
	v_mul_f32_e32 v92, v92, v96
	v_mul_f32_e32 v88, v92, v88
	v_mul_f32_e32 v92, 0xbfb8aa3b, v93
	v_exp_f32_e32 v92, v92
	s_nop 0
	v_add_f32_e32 v92, 1.0, v92
	v_rcp_f32_e32 v92, v92
	s_nop 0
	v_mul_f32_e32 v92, v93, v92
	v_mul_f32_e32 v89, v92, v89
	v_mul_f32_e32 v92, 0xbfb8aa3b, v94
	v_exp_f32_e32 v92, v92
	s_nop 0
	v_add_f32_e32 v92, 1.0, v92
	v_rcp_f32_e32 v92, v92
	s_nop 0
	v_mul_f32_e32 v92, v94, v92
	v_mul_f32_e32 v90, v92, v90
	v_mul_f32_e32 v92, 0xbfb8aa3b, v95
	v_exp_f32_e32 v92, v92
	s_nop 0
	v_add_f32_e32 v92, 1.0, v92
	v_rcp_f32_e32 v92, v92
	s_nop 0
	v_mul_f32_e32 v92, v95, v92
	v_mul_f32_e32 v91, v92, v91
	v_mul_f32_e32 v92, 0xbfb8aa3b, v84
	v_exp_f32_e32 v92, v92
	s_nop 0
	v_add_f32_e32 v92, 1.0, v92
	v_rcp_f32_e32 v92, v92
	s_nop 0
	v_mul_f32_e32 v84, v84, v92
	v_mul_f32_e32 v84, v84, v80
	v_mul_f32_e32 v80, 0xbfb8aa3b, v85
	v_exp_f32_e32 v80, v80
	s_nop 0
	v_add_f32_e32 v80, 1.0, v80
	v_rcp_f32_e32 v80, v80
	s_nop 0
	v_mul_f32_e32 v80, v85, v80
	v_mul_f32_e32 v85, v80, v81
	v_mul_f32_e32 v80, 0xbfb8aa3b, v86
	v_exp_f32_e32 v80, v80
	v_cvt_pk_bf16_f32 v81, v90, v91
	s_nop 0
	v_add_f32_e32 v80, 1.0, v80
	v_rcp_f32_e32 v80, v80
	s_nop 0
	v_mul_f32_e32 v80, v86, v80
	v_mul_f32_e32 v86, v80, v82
	v_mul_f32_e32 v80, 0xbfb8aa3b, v87
	v_exp_f32_e32 v80, v80
	v_cvt_pk_bf16_f32 v82, v84, v85
	v_or_b32_e32 v84, 32, v142
	v_mad_i64_i32 v[84:85], s[16:17], v84, s1, v[112:113]
	v_add_f32_e32 v80, 1.0, v80
	v_rcp_f32_e32 v80, v80
	v_lshl_add_u64 v[84:85], v[84:85], 0, v[114:115]
	v_mul_f32_e32 v80, v87, v80
	v_mul_f32_e32 v83, v80, v83
	v_cvt_pk_bf16_f32 v80, v88, v89
	v_cvt_pk_bf16_f32 v83, v86, v83
	global_store_dwordx4 v[84:85], v[80:83], off
	s_nop 1
	v_mul_f32_e32 v80, 0xbfb8aa3b, v76
	v_exp_f32_e32 v80, v80
	s_nop 0
	v_add_f32_e32 v80, 1.0, v80
	v_rcp_f32_e32 v80, v80
	s_nop 0
	v_mul_f32_e32 v76, v76, v80
	v_mul_f32_e32 v72, v76, v72
	v_mul_f32_e32 v76, 0xbfb8aa3b, v77
	v_exp_f32_e32 v76, v76
	s_nop 0
	v_add_f32_e32 v76, 1.0, v76
	v_rcp_f32_e32 v76, v76
	s_nop 0
	v_mul_f32_e32 v76, v77, v76
	v_mul_f32_e32 v73, v76, v73
	v_mul_f32_e32 v76, 0xbfb8aa3b, v78
	v_exp_f32_e32 v76, v76
	s_nop 0
	v_add_f32_e32 v76, 1.0, v76
	v_rcp_f32_e32 v76, v76
	s_nop 0
	v_mul_f32_e32 v76, v78, v76
	v_mul_f32_e32 v74, v76, v74
	v_mul_f32_e32 v76, 0xbfb8aa3b, v79
	v_exp_f32_e32 v76, v76
	s_nop 0
	v_add_f32_e32 v76, 1.0, v76
	v_rcp_f32_e32 v76, v76
	s_nop 0
	v_mul_f32_e32 v76, v79, v76
	v_mul_f32_e32 v75, v76, v75
	v_mul_f32_e32 v76, 0xbfb8aa3b, v68
	v_exp_f32_e32 v76, v76
	s_nop 0
	v_add_f32_e32 v76, 1.0, v76
	v_rcp_f32_e32 v76, v76
	s_nop 0
	v_mul_f32_e32 v68, v68, v76
	v_mul_f32_e32 v68, v68, v64
	v_mul_f32_e32 v64, 0xbfb8aa3b, v69
	v_exp_f32_e32 v64, v64
	s_nop 0
	v_add_f32_e32 v64, 1.0, v64
	v_rcp_f32_e32 v64, v64
	s_nop 0
	v_mul_f32_e32 v64, v69, v64
	v_mul_f32_e32 v69, v64, v65
	v_mul_f32_e32 v64, 0xbfb8aa3b, v70
	v_exp_f32_e32 v64, v64
	v_cvt_pk_bf16_f32 v65, v74, v75
	s_nop 0
	v_add_f32_e32 v64, 1.0, v64
	v_rcp_f32_e32 v64, v64
	s_nop 0
	v_mul_f32_e32 v64, v70, v64
	v_mul_f32_e32 v70, v64, v66
	v_mul_f32_e32 v64, 0xbfb8aa3b, v71
	v_exp_f32_e32 v64, v64
	v_cvt_pk_bf16_f32 v66, v68, v69
	v_or_b32_e32 v68, 48, v142
	v_mad_i64_i32 v[68:69], s[16:17], v68, s1, v[112:113]
	v_add_f32_e32 v64, 1.0, v64
	v_rcp_f32_e32 v64, v64
	v_lshl_add_u64 v[68:69], v[68:69], 0, v[114:115]
	v_mul_f32_e32 v64, v71, v64
	v_mul_f32_e32 v67, v64, v67
	v_cvt_pk_bf16_f32 v64, v72, v73
	v_cvt_pk_bf16_f32 v67, v70, v67
	global_store_dwordx4 v[68:69], v[64:67], off
	s_nop 1
	v_mul_f32_e32 v65, 0xbfb8aa3b, v60
	v_exp_f32_e32 v65, v65
	v_add_u32_e32 v64, 0x80, v142
	v_add_f32_e32 v65, 1.0, v65
	v_rcp_f32_e32 v65, v65
	s_nop 0
	v_mul_f32_e32 v60, v60, v65
	v_mul_f32_e32 v56, v60, v56
	v_mul_f32_e32 v60, 0xbfb8aa3b, v61
	v_exp_f32_e32 v60, v60
	s_nop 0
	v_add_f32_e32 v60, 1.0, v60
	v_rcp_f32_e32 v60, v60
	s_nop 0
	v_mul_f32_e32 v60, v61, v60
	v_mul_f32_e32 v57, v60, v57
	v_mul_f32_e32 v60, 0xbfb8aa3b, v62
	v_exp_f32_e32 v60, v60
	s_nop 0
	v_add_f32_e32 v60, 1.0, v60
	v_rcp_f32_e32 v60, v60
	s_nop 0
	v_mul_f32_e32 v60, v62, v60
	v_mul_f32_e32 v58, v60, v58
	v_mul_f32_e32 v60, 0xbfb8aa3b, v63
	v_exp_f32_e32 v60, v60
	s_nop 0
	v_add_f32_e32 v60, 1.0, v60
	v_rcp_f32_e32 v60, v60
	s_nop 0
	v_mul_f32_e32 v60, v63, v60
	v_mul_f32_e32 v59, v60, v59
	v_mul_f32_e32 v60, 0xbfb8aa3b, v52
	v_exp_f32_e32 v60, v60
	s_nop 0
; __device__ __forceinline__ unsigned pk2(float lo, float hi) { unsigned r; asm("v_cvt_pk_bf16_f32 %0, %1, %2" : "=v"(r) : "v"(lo), "v"(hi)); return r; }
; __device__ __forceinline__ float sigmoidf_(float x) { return __builtin_amdgcn_rcpf(1.0f + __builtin_amdgcn_exp2f(-1.4426950408889634f * x)); }
; #define PG8_WAIT_V(n) asm volatile("s_waitcnt vmcnt(" #n ")" ::: "memory")
; #define PG8_BAR __builtin_amdgcn_s_barrier()
; template <class Epi>
; __device__ __forceinline__ void gemm_phase(LAS unsigned char* lds, const Gemm g, const StaticOrder& S, const Epi& E) {
;     ...
;         E(acc, cur, wr, wc, fr, fq);
;         if (!has_next) break;
; #pragma unroll
;         for (int a = 0; a < 2; ++a)
; #pragma unroll
;             for (int b = 0; b < 2; ++b)
; #pragma unroll
;                 for (int m = 0; m < 4; ++m)
; #pragma unroll
;                     for (int n = 0; n < 2; ++n) acc[a][b][m][n] = (f32x4){0.f, 0.f, 0.f, 0.f};
;         cur = nxt; cA = nA; cB = nB; ++ui;
;     }
;     PG8_WAIT_V(0);
;     if (wr == 0) PG8_BAR;
;     __device__ __forceinline__ void operator()(const Acc& acc, const Unit& u, int wr, int wc, int fr, int fq) const {
;     ...
;             for (int m = 0; m < 4; ++m) {
;                 float h[8];
; #pragma unroll
;                 for (int n = 0; n < 2; ++n)
; #pragma unroll
;                     for (int j = 0; j < 4; ++j) { const float gv = acc[ai][0][m][n][j], uv = acc[ai][1][m][n][j]; h[n * 4 + j] = gv * sigmoidf_(gv) * uv; }
;                 u32x4 w; w.x = pk2(h[0], h[1]); w.y = pk2(h[2], h[3]); w.z = pk2(h[4], h[5]); w.w = pk2(h[6], h[7]);
;                 *(u32x4*)(H + (size_t)(row0 + ai * 128 + m * 16) * DFF + col0) = w;
	v_add_f32_e32 v60, 1.0, v60
	v_rcp_f32_e32 v60, v60
	s_nop 0
	v_mul_f32_e32 v52, v52, v60
	v_mul_f32_e32 v52, v52, v48
	v_mul_f32_e32 v48, 0xbfb8aa3b, v53
	v_exp_f32_e32 v48, v48
	s_nop 0
	v_add_f32_e32 v48, 1.0, v48
	v_rcp_f32_e32 v48, v48
	s_nop 0
	v_mul_f32_e32 v48, v53, v48
	v_mul_f32_e32 v53, v48, v49
	v_mul_f32_e32 v48, 0xbfb8aa3b, v54
	v_exp_f32_e32 v48, v48
	v_cvt_pk_bf16_f32 v49, v58, v59
	s_nop 0
	v_add_f32_e32 v48, 1.0, v48
	v_rcp_f32_e32 v48, v48
	s_nop 0
	v_mul_f32_e32 v48, v54, v48
	v_mul_f32_e32 v54, v48, v50
	v_mul_f32_e32 v48, 0xbfb8aa3b, v55
	v_exp_f32_e32 v48, v48
	v_cvt_pk_bf16_f32 v50, v52, v53
	v_mad_i64_i32 v[52:53], s[16:17], v64, s1, v[112:113]
	v_add_f32_e32 v48, 1.0, v48
	v_rcp_f32_e32 v48, v48
	v_lshl_add_u64 v[52:53], v[52:53], 0, v[114:115]
	v_mul_f32_e32 v48, v55, v48
	v_mul_f32_e32 v51, v48, v51
	v_cvt_pk_bf16_f32 v48, v56, v57
	v_cvt_pk_bf16_f32 v51, v54, v51
	global_store_dwordx4 v[52:53], v[48:51], off
	s_nop 1
	v_mul_f32_e32 v48, 0xbfb8aa3b, v44
	v_exp_f32_e32 v48, v48
	s_nop 0
	v_add_f32_e32 v48, 1.0, v48
	v_rcp_f32_e32 v48, v48
	s_nop 0
	v_mul_f32_e32 v44, v44, v48
	v_mul_f32_e32 v40, v44, v40
	v_mul_f32_e32 v44, 0xbfb8aa3b, v45
	v_exp_f32_e32 v44, v44
	s_nop 0
	v_add_f32_e32 v44, 1.0, v44
	v_rcp_f32_e32 v44, v44
	s_nop 0
	v_mul_f32_e32 v44, v45, v44
	v_mul_f32_e32 v41, v44, v41
	v_mul_f32_e32 v44, 0xbfb8aa3b, v46
	v_exp_f32_e32 v44, v44
	s_nop 0
	v_add_f32_e32 v44, 1.0, v44
	v_rcp_f32_e32 v44, v44
	s_nop 0
	v_mul_f32_e32 v44, v46, v44
	v_mul_f32_e32 v42, v44, v42
	v_mul_f32_e32 v44, 0xbfb8aa3b, v47
	v_exp_f32_e32 v44, v44
	s_nop 0
	v_add_f32_e32 v44, 1.0, v44
	v_rcp_f32_e32 v44, v44
	s_nop 0
	v_mul_f32_e32 v44, v47, v44
	v_mul_f32_e32 v43, v44, v43
	v_mul_f32_e32 v44, 0xbfb8aa3b, v36
	v_exp_f32_e32 v44, v44
	s_nop 0
	v_add_f32_e32 v44, 1.0, v44
	v_rcp_f32_e32 v44, v44
	s_nop 0
	v_mul_f32_e32 v36, v36, v44
	v_mul_f32_e32 v36, v36, v32
	v_mul_f32_e32 v32, 0xbfb8aa3b, v37
	v_exp_f32_e32 v32, v32
	s_nop 0
	v_add_f32_e32 v32, 1.0, v32
	v_rcp_f32_e32 v32, v32
	s_nop 0
	v_mul_f32_e32 v32, v37, v32
	v_mul_f32_e32 v37, v32, v33
	v_mul_f32_e32 v32, 0xbfb8aa3b, v38
	v_exp_f32_e32 v32, v32
	v_cvt_pk_bf16_f32 v33, v42, v43
	s_nop 0
	v_add_f32_e32 v32, 1.0, v32
	v_rcp_f32_e32 v32, v32
	s_nop 0
	v_mul_f32_e32 v32, v38, v32
	v_mul_f32_e32 v38, v32, v34
	v_mul_f32_e32 v32, 0xbfb8aa3b, v39
	v_exp_f32_e32 v32, v32
	v_cvt_pk_bf16_f32 v34, v36, v37
	v_add_u32_e32 v36, 0x90, v142
	v_mad_i64_i32 v[36:37], s[16:17], v36, s1, v[112:113]
	v_add_f32_e32 v32, 1.0, v32
	v_rcp_f32_e32 v32, v32
	v_lshl_add_u64 v[36:37], v[36:37], 0, v[114:115]
	v_mul_f32_e32 v32, v39, v32
	v_mul_f32_e32 v35, v32, v35
	v_cvt_pk_bf16_f32 v32, v40, v41
	v_cvt_pk_bf16_f32 v35, v38, v35
	global_store_dwordx4 v[36:37], v[32:35], off
	s_nop 1
	v_mul_f32_e32 v32, 0xbfb8aa3b, v28
	v_exp_f32_e32 v32, v32
	s_nop 0
	v_add_f32_e32 v32, 1.0, v32
	v_rcp_f32_e32 v32, v32
	s_nop 0
	v_mul_f32_e32 v28, v28, v32
	v_mul_f32_e32 v24, v28, v24
	v_mul_f32_e32 v28, 0xbfb8aa3b, v29
	v_exp_f32_e32 v28, v28
	s_nop 0
	v_add_f32_e32 v28, 1.0, v28
	v_rcp_f32_e32 v28, v28
	s_nop 0
	v_mul_f32_e32 v28, v29, v28
	v_mul_f32_e32 v25, v28, v25
	v_mul_f32_e32 v28, 0xbfb8aa3b, v30
	v_exp_f32_e32 v28, v28
	s_nop 0
	v_add_f32_e32 v28, 1.0, v28
	v_rcp_f32_e32 v28, v28
	s_nop 0
	v_mul_f32_e32 v28, v30, v28
	v_mul_f32_e32 v26, v28, v26
	v_mul_f32_e32 v28, 0xbfb8aa3b, v31
	v_exp_f32_e32 v28, v28
	s_nop 0
	v_add_f32_e32 v28, 1.0, v28
	v_rcp_f32_e32 v28, v28
	s_nop 0
	v_mul_f32_e32 v28, v31, v28
	v_mul_f32_e32 v27, v28, v27
	v_mul_f32_e32 v28, 0xbfb8aa3b, v20
	v_exp_f32_e32 v28, v28
	s_nop 0
	v_add_f32_e32 v28, 1.0, v28
	v_rcp_f32_e32 v28, v28
	s_nop 0
	v_mul_f32_e32 v20, v20, v28
	v_mul_f32_e32 v20, v20, v16
	v_mul_f32_e32 v16, 0xbfb8aa3b, v21
	v_exp_f32_e32 v16, v16
	s_nop 0
	v_add_f32_e32 v16, 1.0, v16
	v_rcp_f32_e32 v16, v16
	s_nop 0
	v_mul_f32_e32 v16, v21, v16
	v_mul_f32_e32 v21, v16, v17
	v_mul_f32_e32 v16, 0xbfb8aa3b, v22
	v_exp_f32_e32 v16, v16
	v_cvt_pk_bf16_f32 v17, v26, v27
	s_nop 0
	v_add_f32_e32 v16, 1.0, v16
	v_rcp_f32_e32 v16, v16
	s_nop 0
	v_mul_f32_e32 v16, v22, v16
	v_mul_f32_e32 v22, v16, v18
	v_mul_f32_e32 v16, 0xbfb8aa3b, v23
	v_exp_f32_e32 v16, v16
	v_cvt_pk_bf16_f32 v18, v20, v21
	v_add_u32_e32 v20, 0xa0, v142
	v_mad_i64_i32 v[20:21], s[16:17], v20, s1, v[112:113]
	v_add_f32_e32 v16, 1.0, v16
	v_rcp_f32_e32 v16, v16
	v_lshl_add_u64 v[20:21], v[20:21], 0, v[114:115]
	v_mul_f32_e32 v16, v23, v16
	v_mul_f32_e32 v19, v16, v19
	v_cvt_pk_bf16_f32 v16, v24, v25
	v_cvt_pk_bf16_f32 v19, v22, v19
	global_store_dwordx4 v[20:21], v[16:19], off
	s_nop 1
	v_mul_f32_e32 v16, 0xbfb8aa3b, v12
	v_exp_f32_e32 v16, v16
	s_nop 0
	v_add_f32_e32 v16, 1.0, v16
	v_rcp_f32_e32 v16, v16
	s_nop 0
	v_mul_f32_e32 v12, v12, v16
	v_mul_f32_e32 v8, v12, v8
	v_mul_f32_e32 v12, 0xbfb8aa3b, v13
	v_exp_f32_e32 v12, v12
	s_nop 0
	v_add_f32_e32 v12, 1.0, v12
	v_rcp_f32_e32 v12, v12
	s_nop 0
	v_mul_f32_e32 v12, v13, v12
	v_mul_f32_e32 v9, v12, v9
	v_mul_f32_e32 v12, 0xbfb8aa3b, v14
	v_exp_f32_e32 v12, v12
	s_nop 0
	v_add_f32_e32 v12, 1.0, v12
	v_rcp_f32_e32 v12, v12
	s_nop 0
	v_mul_f32_e32 v12, v14, v12
	v_mul_f32_e32 v10, v12, v10
	v_mul_f32_e32 v12, 0xbfb8aa3b, v15
	v_exp_f32_e32 v12, v12
	s_nop 0
	v_add_f32_e32 v12, 1.0, v12
	v_rcp_f32_e32 v12, v12
	s_nop 0
	v_mul_f32_e32 v12, v15, v12
	v_mul_f32_e32 v11, v12, v11
	v_mul_f32_e32 v12, 0xbfb8aa3b, v4
	v_exp_f32_e32 v12, v12
	s_nop 0
	v_add_f32_e32 v12, 1.0, v12
	v_rcp_f32_e32 v12, v12
	s_nop 0
	v_mul_f32_e32 v4, v4, v12
	v_mul_f32_e32 v4, v4, v0
	v_mul_f32_e32 v0, 0xbfb8aa3b, v5
	v_exp_f32_e32 v0, v0
	s_nop 0
	v_add_f32_e32 v0, 1.0, v0
	v_rcp_f32_e32 v0, v0
	s_nop 0
	v_mul_f32_e32 v0, v5, v0
	v_mul_f32_e32 v5, v0, v1
	v_mul_f32_e32 v0, 0xbfb8aa3b, v6
	v_exp_f32_e32 v0, v0
	v_cvt_pk_bf16_f32 v1, v10, v11
	s_nop 0
	v_add_f32_e32 v0, 1.0, v0
	v_rcp_f32_e32 v0, v0
	s_nop 0
	v_mul_f32_e32 v0, v6, v0
	v_mul_f32_e32 v6, v0, v2
	v_mul_f32_e32 v0, 0xbfb8aa3b, v7
	v_exp_f32_e32 v0, v0
	v_cvt_pk_bf16_f32 v2, v4, v5
	v_add_u32_e32 v4, 0xb0, v142
	v_mad_i64_i32 v[4:5], s[16:17], v4, s1, v[112:113]
	v_add_f32_e32 v0, 1.0, v0
	v_rcp_f32_e32 v0, v0
	v_lshl_add_u64 v[4:5], v[4:5], 0, v[114:115]
	s_mov_b64 s[16:17], s[10:11]
	v_mul_f32_e32 v0, v7, v0
	v_mul_f32_e32 v3, v0, v3
	v_cvt_pk_bf16_f32 v0, v8, v9
	v_cvt_pk_bf16_f32 v3, v6, v3
	global_store_dwordx4 v[4:5], v[0:3], off
	s_cbranch_vccz .LBB0_718
	s_waitcnt vmcnt(0)
	s_cmpk_gt_u32 s23, 0xff
	s_cbranch_scc1 .LBB0_725
	s_barrier
